# MFMA order: same-accumulator pairs back-to-back, pair boundaries share one operand (alternating k order), on combo4
# baseline (speedup 1.0000x reference)
.LBB0_175:
	s_add_i32 s29, s29, 2
	s_mov_b32 s44, s29
	s_ashr_i32 s45, s44, 31
	s_lshl_b64 s[82:83], s[44:45], 7
	s_add_u32 s45, s82, 0x100
	s_addc_u32 s81, s83, 0
	s_add_u32 s84, s42, s45
	s_addc_u32 s85, s43, s81
	s_add_u32 s86, s40, s45
	s_addc_u32 s81, s41, s81
	s_cmp_eq_u32 s44, 14
	s_cselect_b32 s45, s75, s85
	s_cselect_b32 s44, s76, s84
	s_cselect_b32 s85, s31, s81
	s_cselect_b32 s84, s74, s86
	s_add_u32 s82, s42, s82
	s_addc_u32 s83, s43, s83
	v_lshl_add_u64 v[212:213], s[82:83], 0, v[130:131]
	s_mov_b32 m0, s66
	v_lshl_add_u64 v[214:215], v[212:213], 0, s[22:23]
	global_load_lds_dwordx4 v[214:215], off
	v_lshl_add_u64 v[212:213], v[212:213], 0, s[24:25]
	s_mov_b32 m0, s67
	s_nop 0
	global_load_lds_dwordx4 v[212:213], off
	ds_read_b128 v[146:149], v141
	ds_read_b128 v[150:153], v141 offset:1024
	ds_read_b128 v[154:157], v141 offset:2048
	ds_read_b128 v[158:161], v141 offset:3072
	ds_read_b128 v[162:165], v142
	ds_read_b128 v[166:169], v142 offset:1024
	ds_read_b128 v[170:173], v142 offset:2048
	ds_read_b128 v[174:177], v142 offset:3072
	ds_read_b128 v[178:181], v143
	ds_read_b128 v[182:185], v143 offset:1024
	ds_read_b128 v[186:189], v143 offset:2048
	ds_read_b128 v[190:193], v143 offset:3072
	ds_read_b128 v[194:197], v143 offset:4096
	ds_read_b128 v[198:201], v143 offset:5120
	ds_read_b128 v[202:205], v143 offset:6144
	ds_read_b128 v[206:209], v143 offset:7168
	s_waitcnt vmcnt(8)
	s_waitcnt lgkmcnt(0)
	s_barrier
	s_waitcnt lgkmcnt(0)
	v_mfma_f32_16x16x32_bf16 v[124:127], v[146:149], v[178:181], v[124:127]
	v_mfma_f32_16x16x32_bf16 v[124:127], v[150:153], v[182:185], v[124:127]
	v_mfma_f32_16x16x32_bf16 v[112:115], v[158:161], v[182:185], v[112:115]
	v_mfma_f32_16x16x32_bf16 v[112:115], v[154:157], v[178:181], v[112:115]
	v_mfma_f32_16x16x32_bf16 v[120:123], v[162:165], v[178:181], v[120:123]
	v_mfma_f32_16x16x32_bf16 v[120:123], v[166:169], v[182:185], v[120:123]
	v_mfma_f32_16x16x32_bf16 v[116:119], v[174:177], v[182:185], v[116:119]
	v_mfma_f32_16x16x32_bf16 v[116:119], v[170:173], v[178:181], v[116:119]
	v_mfma_f32_16x16x32_bf16 v[100:103], v[170:173], v[186:189], v[100:103]
	v_mfma_f32_16x16x32_bf16 v[100:103], v[174:177], v[190:193], v[100:103]
	v_mfma_f32_16x16x32_bf16 v[104:107], v[166:169], v[190:193], v[104:107]
	v_mfma_f32_16x16x32_bf16 v[104:107], v[162:165], v[186:189], v[104:107]
	v_mfma_f32_16x16x32_bf16 v[96:99], v[154:157], v[186:189], v[96:99]
	v_mfma_f32_16x16x32_bf16 v[96:99], v[158:161], v[190:193], v[96:99]
	v_mfma_f32_16x16x32_bf16 v[108:111], v[150:153], v[190:193], v[108:111]
	v_mfma_f32_16x16x32_bf16 v[108:111], v[146:149], v[186:189], v[108:111]
	v_mfma_f32_16x16x32_bf16 v[92:95], v[146:149], v[194:197], v[92:95]
	v_mfma_f32_16x16x32_bf16 v[92:95], v[150:153], v[198:201], v[92:95]
	v_mfma_f32_16x16x32_bf16 v[80:83], v[158:161], v[198:201], v[80:83]
	v_mfma_f32_16x16x32_bf16 v[80:83], v[154:157], v[194:197], v[80:83]
	v_mfma_f32_16x16x32_bf16 v[88:91], v[162:165], v[194:197], v[88:91]
	v_mfma_f32_16x16x32_bf16 v[88:91], v[166:169], v[198:201], v[88:91]
	v_mfma_f32_16x16x32_bf16 v[84:87], v[174:177], v[198:201], v[84:87]
	v_mfma_f32_16x16x32_bf16 v[84:87], v[170:173], v[194:197], v[84:87]
	v_mfma_f32_16x16x32_bf16 v[68:71], v[170:173], v[202:205], v[68:71]
	v_mfma_f32_16x16x32_bf16 v[68:71], v[174:177], v[206:209], v[68:71]
	v_mfma_f32_16x16x32_bf16 v[72:75], v[166:169], v[206:209], v[72:75]
	v_mfma_f32_16x16x32_bf16 v[72:75], v[162:165], v[202:205], v[72:75]
	v_mfma_f32_16x16x32_bf16 v[64:67], v[154:157], v[202:205], v[64:67]
	v_mfma_f32_16x16x32_bf16 v[64:67], v[158:161], v[206:209], v[64:67]
	v_mfma_f32_16x16x32_bf16 v[76:79], v[150:153], v[206:209], v[76:79]
	v_mfma_f32_16x16x32_bf16 v[76:79], v[146:149], v[202:205], v[76:79]
	s_barrier
	s_mov_b32 m0, s68
	v_lshl_add_u64 v[212:213], s[84:85], 0, v[128:129]
	global_load_lds_dwordx4 v[212:213], off
	v_lshl_add_u64 v[214:215], v[212:213], 0, s[0:1]
	s_mov_b32 m0, s69
	s_nop 0
	global_load_lds_dwordx4 v[214:215], off
	v_lshl_add_u64 v[214:215], v[212:213], 0, s[2:3]
	s_mov_b32 m0, s70
	s_nop 0
	global_load_lds_dwordx4 v[214:215], off
	v_lshl_add_u64 v[214:215], v[212:213], 0, s[8:9]
	s_mov_b32 m0, s71
	s_nop 0
	global_load_lds_dwordx4 v[214:215], off
	v_lshl_add_u64 v[214:215], s[44:45], 0, v[130:131]
	s_mov_b32 m0, s39
	v_lshl_add_u64 v[216:217], v[214:215], 0, s[0:1]
	global_load_lds_dwordx4 v[214:215], off
	s_mov_b32 m0, s56
	s_nop 0
	global_load_lds_dwordx4 v[216:217], off
	ds_read_b128 v[178:181], v143 offset:16384
	ds_read_b128 v[182:185], v143 offset:17408
	ds_read_b128 v[186:189], v143 offset:18432
	ds_read_b128 v[190:193], v143 offset:19456
	ds_read_b128 v[194:197], v143 offset:20480
	ds_read_b128 v[198:201], v143 offset:21504
	ds_read_b128 v[202:205], v143 offset:22528
	ds_read_b128 v[206:209], v143 offset:23552
	s_waitcnt vmcnt(8)
	s_waitcnt lgkmcnt(0)
	s_barrier
	s_waitcnt lgkmcnt(0)
	v_mfma_f32_16x16x32_bf16 v[60:63], v[146:149], v[178:181], v[60:63]
	v_mfma_f32_16x16x32_bf16 v[60:63], v[150:153], v[182:185], v[60:63]
	v_mfma_f32_16x16x32_bf16 v[48:51], v[158:161], v[182:185], v[48:51]
	v_mfma_f32_16x16x32_bf16 v[48:51], v[154:157], v[178:181], v[48:51]
	v_mfma_f32_16x16x32_bf16 v[56:59], v[162:165], v[178:181], v[56:59]
	v_mfma_f32_16x16x32_bf16 v[56:59], v[166:169], v[182:185], v[56:59]
	v_mfma_f32_16x16x32_bf16 v[52:55], v[174:177], v[182:185], v[52:55]
	v_mfma_f32_16x16x32_bf16 v[52:55], v[170:173], v[178:181], v[52:55]
	v_mfma_f32_16x16x32_bf16 v[36:39], v[170:173], v[186:189], v[36:39]
	v_mfma_f32_16x16x32_bf16 v[36:39], v[174:177], v[190:193], v[36:39]
	v_mfma_f32_16x16x32_bf16 v[40:43], v[166:169], v[190:193], v[40:43]
	v_mfma_f32_16x16x32_bf16 v[40:43], v[162:165], v[186:189], v[40:43]
	v_mfma_f32_16x16x32_bf16 v[32:35], v[154:157], v[186:189], v[32:35]
	v_mfma_f32_16x16x32_bf16 v[32:35], v[158:161], v[190:193], v[32:35]
	v_mfma_f32_16x16x32_bf16 v[44:47], v[150:153], v[190:193], v[44:47]
	v_mfma_f32_16x16x32_bf16 v[44:47], v[146:149], v[186:189], v[44:47]
	v_mfma_f32_16x16x32_bf16 v[28:31], v[146:149], v[194:197], v[28:31]
	v_mfma_f32_16x16x32_bf16 v[28:31], v[150:153], v[198:201], v[28:31]
	v_mfma_f32_16x16x32_bf16 v[16:19], v[158:161], v[198:201], v[16:19]
	v_mfma_f32_16x16x32_bf16 v[16:19], v[154:157], v[194:197], v[16:19]
	v_mfma_f32_16x16x32_bf16 v[24:27], v[162:165], v[194:197], v[24:27]
	v_mfma_f32_16x16x32_bf16 v[24:27], v[166:169], v[198:201], v[24:27]
	v_mfma_f32_16x16x32_bf16 v[20:23], v[174:177], v[198:201], v[20:23]
	v_mfma_f32_16x16x32_bf16 v[20:23], v[170:173], v[194:197], v[20:23]
	v_mfma_f32_16x16x32_bf16 v[4:7], v[170:173], v[202:205], v[4:7]
	v_mfma_f32_16x16x32_bf16 v[4:7], v[174:177], v[206:209], v[4:7]
	v_mfma_f32_16x16x32_bf16 v[8:11], v[166:169], v[206:209], v[8:11]
	v_mfma_f32_16x16x32_bf16 v[8:11], v[162:165], v[202:205], v[8:11]
	v_mfma_f32_16x16x32_bf16 v[0:3], v[154:157], v[202:205], v[0:3]
	v_mfma_f32_16x16x32_bf16 v[0:3], v[158:161], v[206:209], v[0:3]
	v_mfma_f32_16x16x32_bf16 v[12:15], v[150:153], v[206:209], v[12:15]
	v_mfma_f32_16x16x32_bf16 v[12:15], v[146:149], v[202:205], v[12:15]
	s_barrier
	s_mov_b32 m0, s57
	v_lshl_add_u64 v[216:217], v[214:215], 0, s[2:3]
	global_load_lds_dwordx4 v[216:217], off
	v_lshl_add_u64 v[216:217], v[214:215], 0, s[8:9]
	s_mov_b32 m0, s58
	s_nop 0
	global_load_lds_dwordx4 v[216:217], off
	ds_read_b128 v[146:149], v144
	ds_read_b128 v[150:153], v144 offset:1024
	ds_read_b128 v[154:157], v144 offset:2048
	ds_read_b128 v[158:161], v144 offset:3072
	ds_read_b128 v[162:165], v136
	ds_read_b128 v[166:169], v136 offset:1024
	ds_read_b128 v[170:173], v136 offset:2048
	ds_read_b128 v[174:177], v136 offset:3072
	ds_read_b128 v[178:181], v143 offset:32768
	ds_read_b128 v[182:185], v143 offset:33792
	ds_read_b128 v[186:189], v143 offset:34816
	ds_read_b128 v[190:193], v143 offset:35840
	ds_read_b128 v[194:197], v143 offset:36864
	ds_read_b128 v[198:201], v143 offset:37888
	ds_read_b128 v[202:205], v143 offset:38912
	ds_read_b128 v[206:209], v143 offset:39936
	s_waitcnt vmcnt(8)
	s_waitcnt lgkmcnt(0)
	s_barrier
	s_waitcnt lgkmcnt(0)
	v_mfma_f32_16x16x32_bf16 v[124:127], v[146:149], v[178:181], v[124:127]
	v_mfma_f32_16x16x32_bf16 v[124:127], v[150:153], v[182:185], v[124:127]
	v_mfma_f32_16x16x32_bf16 v[112:115], v[158:161], v[182:185], v[112:115]
	v_mfma_f32_16x16x32_bf16 v[112:115], v[154:157], v[178:181], v[112:115]
	v_mfma_f32_16x16x32_bf16 v[120:123], v[162:165], v[178:181], v[120:123]
	v_mfma_f32_16x16x32_bf16 v[120:123], v[166:169], v[182:185], v[120:123]
	v_mfma_f32_16x16x32_bf16 v[116:119], v[174:177], v[182:185], v[116:119]
	v_mfma_f32_16x16x32_bf16 v[116:119], v[170:173], v[178:181], v[116:119]
	v_mfma_f32_16x16x32_bf16 v[100:103], v[170:173], v[186:189], v[100:103]
	v_mfma_f32_16x16x32_bf16 v[100:103], v[174:177], v[190:193], v[100:103]
	v_mfma_f32_16x16x32_bf16 v[104:107], v[166:169], v[190:193], v[104:107]
	v_mfma_f32_16x16x32_bf16 v[104:107], v[162:165], v[186:189], v[104:107]
	v_mfma_f32_16x16x32_bf16 v[96:99], v[154:157], v[186:189], v[96:99]
	v_mfma_f32_16x16x32_bf16 v[96:99], v[158:161], v[190:193], v[96:99]
	v_mfma_f32_16x16x32_bf16 v[108:111], v[150:153], v[190:193], v[108:111]
	v_mfma_f32_16x16x32_bf16 v[108:111], v[146:149], v[186:189], v[108:111]
	v_mfma_f32_16x16x32_bf16 v[92:95], v[146:149], v[194:197], v[92:95]
	v_mfma_f32_16x16x32_bf16 v[92:95], v[150:153], v[198:201], v[92:95]
	v_mfma_f32_16x16x32_bf16 v[80:83], v[158:161], v[198:201], v[80:83]
	v_mfma_f32_16x16x32_bf16 v[80:83], v[154:157], v[194:197], v[80:83]
	v_mfma_f32_16x16x32_bf16 v[88:91], v[162:165], v[194:197], v[88:91]
	v_mfma_f32_16x16x32_bf16 v[88:91], v[166:169], v[198:201], v[88:91]
	v_mfma_f32_16x16x32_bf16 v[84:87], v[174:177], v[198:201], v[84:87]
	v_mfma_f32_16x16x32_bf16 v[84:87], v[170:173], v[194:197], v[84:87]
	v_mfma_f32_16x16x32_bf16 v[68:71], v[170:173], v[202:205], v[68:71]
	v_mfma_f32_16x16x32_bf16 v[68:71], v[174:177], v[206:209], v[68:71]
	v_mfma_f32_16x16x32_bf16 v[72:75], v[166:169], v[206:209], v[72:75]
	v_mfma_f32_16x16x32_bf16 v[72:75], v[162:165], v[202:205], v[72:75]
	v_mfma_f32_16x16x32_bf16 v[64:67], v[154:157], v[202:205], v[64:67]
	v_mfma_f32_16x16x32_bf16 v[64:67], v[158:161], v[206:209], v[64:67]
	v_mfma_f32_16x16x32_bf16 v[76:79], v[150:153], v[206:209], v[76:79]
	v_mfma_f32_16x16x32_bf16 v[76:79], v[146:149], v[202:205], v[76:79]
	s_barrier
	s_mov_b32 m0, s77
	v_lshl_add_u64 v[216:217], v[212:213], 0, s[18:19]
	global_load_lds_dwordx4 v[216:217], off
	v_lshl_add_u64 v[216:217], v[212:213], 0, s[20:21]
	s_mov_b32 m0, s78
	s_nop 0
	global_load_lds_dwordx4 v[216:217], off
	v_lshl_add_u64 v[216:217], v[212:213], 0, s[22:23]
	s_mov_b32 m0, s79
	v_lshl_add_u64 v[212:213], v[212:213], 0, s[24:25]
	global_load_lds_dwordx4 v[216:217], off
	s_mov_b32 m0, s80
	s_nop 0
	global_load_lds_dwordx4 v[212:213], off
	v_lshl_add_u64 v[212:213], v[214:215], 0, s[18:19]
	s_mov_b32 m0, s60
	s_nop 0
	global_load_lds_dwordx4 v[212:213], off
	v_lshl_add_u64 v[212:213], v[214:215], 0, s[20:21]
	s_mov_b32 m0, s61
	s_nop 0
	global_load_lds_dwordx4 v[212:213], off
	ds_read_b128 v[178:181], v143 offset:49152
	ds_read_b128 v[182:185], v143 offset:50176
	ds_read_b128 v[186:189], v143 offset:51200
	ds_read_b128 v[190:193], v143 offset:52224
	ds_read_b128 v[194:197], v143 offset:53248
	ds_read_b128 v[198:201], v143 offset:54272
	ds_read_b128 v[202:205], v143 offset:55296
	ds_read_b128 v[206:209], v143 offset:56320
	s_waitcnt vmcnt(8)
	s_waitcnt lgkmcnt(0)
	s_barrier
	s_waitcnt lgkmcnt(0)
	v_mfma_f32_16x16x32_bf16 v[60:63], v[146:149], v[178:181], v[60:63]
	v_mfma_f32_16x16x32_bf16 v[60:63], v[150:153], v[182:185], v[60:63]
	v_mfma_f32_16x16x32_bf16 v[48:51], v[158:161], v[182:185], v[48:51]
	v_mfma_f32_16x16x32_bf16 v[48:51], v[154:157], v[178:181], v[48:51]
	v_mfma_f32_16x16x32_bf16 v[56:59], v[162:165], v[178:181], v[56:59]
	v_mfma_f32_16x16x32_bf16 v[56:59], v[166:169], v[182:185], v[56:59]
	v_mfma_f32_16x16x32_bf16 v[52:55], v[174:177], v[182:185], v[52:55]
	v_mfma_f32_16x16x32_bf16 v[52:55], v[170:173], v[178:181], v[52:55]
	v_mfma_f32_16x16x32_bf16 v[36:39], v[170:173], v[186:189], v[36:39]
	v_mfma_f32_16x16x32_bf16 v[36:39], v[174:177], v[190:193], v[36:39]
	v_mfma_f32_16x16x32_bf16 v[40:43], v[166:169], v[190:193], v[40:43]
	v_mfma_f32_16x16x32_bf16 v[40:43], v[162:165], v[186:189], v[40:43]
	v_mfma_f32_16x16x32_bf16 v[32:35], v[154:157], v[186:189], v[32:35]
	v_mfma_f32_16x16x32_bf16 v[32:35], v[158:161], v[190:193], v[32:35]
	v_mfma_f32_16x16x32_bf16 v[44:47], v[150:153], v[190:193], v[44:47]
	v_mfma_f32_16x16x32_bf16 v[44:47], v[146:149], v[186:189], v[44:47]
	v_mfma_f32_16x16x32_bf16 v[28:31], v[146:149], v[194:197], v[28:31]
	v_mfma_f32_16x16x32_bf16 v[28:31], v[150:153], v[198:201], v[28:31]
	v_mfma_f32_16x16x32_bf16 v[16:19], v[158:161], v[198:201], v[16:19]
	v_mfma_f32_16x16x32_bf16 v[16:19], v[154:157], v[194:197], v[16:19]
	v_mfma_f32_16x16x32_bf16 v[24:27], v[162:165], v[194:197], v[24:27]
	v_mfma_f32_16x16x32_bf16 v[24:27], v[166:169], v[198:201], v[24:27]
	v_mfma_f32_16x16x32_bf16 v[20:23], v[174:177], v[198:201], v[20:23]
	v_mfma_f32_16x16x32_bf16 v[20:23], v[170:173], v[194:197], v[20:23]
	v_mfma_f32_16x16x32_bf16 v[4:7], v[170:173], v[202:205], v[4:7]
	v_mfma_f32_16x16x32_bf16 v[4:7], v[174:177], v[206:209], v[4:7]
	v_mfma_f32_16x16x32_bf16 v[8:11], v[166:169], v[206:209], v[8:11]
	v_mfma_f32_16x16x32_bf16 v[8:11], v[162:165], v[202:205], v[8:11]
	v_mfma_f32_16x16x32_bf16 v[0:3], v[154:157], v[202:205], v[0:3]
	v_mfma_f32_16x16x32_bf16 v[0:3], v[158:161], v[206:209], v[0:3]
	v_mfma_f32_16x16x32_bf16 v[12:15], v[150:153], v[206:209], v[12:15]
	v_mfma_f32_16x16x32_bf16 v[12:15], v[146:149], v[202:205], v[12:15]
	s_barrier
	s_cmp_gt_u32 s29, 13
	s_cbranch_scc0 .LBB0_175
	s_and_b64 vcc, exec, s[26:27]
	s_cbranch_vccz .LBB0_178
	s_barrier

.LBB0_255:
	s_add_i32 s73, s73, 2
	s_mov_b32 s74, s73
	s_ashr_i32 s75, s74, 31
	s_lshl_b64 s[76:77], s[74:75], 7
	s_add_u32 s75, s76, 0x100
	s_addc_u32 s78, s77, 0
	s_add_u32 s79, s40, s75
	s_addc_u32 s80, s41, s78
	s_add_u32 s81, s38, s75
	s_addc_u32 s78, s39, s78
	s_cmp_eq_u32 s74, 42
	s_cselect_b32 s75, s1, s80
	s_cselect_b32 s74, s0, s79
	s_cselect_b32 s79, s43, s78
	s_cselect_b32 s78, s42, s81
	v_lshl_add_u64 v[208:209], v[136:137], 0, s[76:77]
	v_lshl_add_u64 v[212:213], v[208:209], 0, s[20:21]
	s_add_i32 m0, s53, 0xc000
	s_nop 0
	global_load_lds_dwordx4 v[212:213], off
	v_lshl_add_u64 v[208:209], v[208:209], 0, s[22:23]
	s_add_i32 m0, s53, 0xe000
	s_nop 0
	global_load_lds_dwordx4 v[208:209], off
	ds_read_b128 v[144:147], v141
	ds_read_b128 v[148:151], v141 offset:1024
	ds_read_b128 v[152:155], v141 offset:2048
	ds_read_b128 v[156:159], v141 offset:3072
	ds_read_b128 v[160:163], v142
	ds_read_b128 v[164:167], v142 offset:1024
	ds_read_b128 v[168:171], v142 offset:2048
	ds_read_b128 v[172:175], v142 offset:3072
	ds_read_b128 v[176:179], v143
	ds_read_b128 v[180:183], v143 offset:1024
	ds_read_b128 v[184:187], v143 offset:2048
	ds_read_b128 v[188:191], v143 offset:3072
	ds_read_b128 v[192:195], v143 offset:4096
	ds_read_b128 v[196:199], v143 offset:5120
	ds_read_b128 v[200:203], v143 offset:6144
	ds_read_b128 v[204:207], v143 offset:7168
	s_waitcnt vmcnt(8)
	s_waitcnt lgkmcnt(0)
	s_barrier
	s_waitcnt lgkmcnt(0)
	v_mfma_f32_16x16x32_bf16 v[124:127], v[144:147], v[176:179], v[124:127]
	v_mfma_f32_16x16x32_bf16 v[124:127], v[148:151], v[180:183], v[124:127]
	v_mfma_f32_16x16x32_bf16 v[120:123], v[156:159], v[180:183], v[120:123]
	v_mfma_f32_16x16x32_bf16 v[120:123], v[152:155], v[176:179], v[120:123]
	v_mfma_f32_16x16x32_bf16 v[108:111], v[160:163], v[176:179], v[108:111]
	v_mfma_f32_16x16x32_bf16 v[108:111], v[164:167], v[180:183], v[108:111]
	v_mfma_f32_16x16x32_bf16 v[104:107], v[172:175], v[180:183], v[104:107]
	v_mfma_f32_16x16x32_bf16 v[104:107], v[168:171], v[176:179], v[104:107]
	v_mfma_f32_16x16x32_bf16 v[88:91], v[168:171], v[184:187], v[88:91]
	v_mfma_f32_16x16x32_bf16 v[88:91], v[172:175], v[188:191], v[88:91]
	v_mfma_f32_16x16x32_bf16 v[92:95], v[164:167], v[188:191], v[92:95]
	v_mfma_f32_16x16x32_bf16 v[92:95], v[160:163], v[184:187], v[92:95]
	v_mfma_f32_16x16x32_bf16 v[112:115], v[152:155], v[184:187], v[112:115]
	v_mfma_f32_16x16x32_bf16 v[112:115], v[156:159], v[188:191], v[112:115]
	v_mfma_f32_16x16x32_bf16 v[116:119], v[148:151], v[188:191], v[116:119]
	v_mfma_f32_16x16x32_bf16 v[116:119], v[144:147], v[184:187], v[116:119]
	v_mfma_f32_16x16x32_bf16 v[100:103], v[144:147], v[192:195], v[100:103]
	v_mfma_f32_16x16x32_bf16 v[100:103], v[148:151], v[196:199], v[100:103]
	v_mfma_f32_16x16x32_bf16 v[96:99], v[156:159], v[196:199], v[96:99]
	v_mfma_f32_16x16x32_bf16 v[96:99], v[152:155], v[192:195], v[96:99]
	v_mfma_f32_16x16x32_bf16 v[76:79], v[160:163], v[192:195], v[76:79]
	v_mfma_f32_16x16x32_bf16 v[76:79], v[164:167], v[196:199], v[76:79]
	v_mfma_f32_16x16x32_bf16 v[72:75], v[172:175], v[196:199], v[72:75]
	v_mfma_f32_16x16x32_bf16 v[72:75], v[168:171], v[192:195], v[72:75]
	v_mfma_f32_16x16x32_bf16 v[64:67], v[168:171], v[200:203], v[64:67]
	v_mfma_f32_16x16x32_bf16 v[64:67], v[172:175], v[204:207], v[64:67]
	v_mfma_f32_16x16x32_bf16 v[68:71], v[164:167], v[204:207], v[68:71]
	v_mfma_f32_16x16x32_bf16 v[68:71], v[160:163], v[200:203], v[68:71]
	v_mfma_f32_16x16x32_bf16 v[80:83], v[152:155], v[200:203], v[80:83]
	v_mfma_f32_16x16x32_bf16 v[80:83], v[156:159], v[204:207], v[80:83]
	v_mfma_f32_16x16x32_bf16 v[84:87], v[148:151], v[204:207], v[84:87]
	v_mfma_f32_16x16x32_bf16 v[84:87], v[144:147], v[200:203], v[84:87]
	s_barrier
	s_add_i32 s76, s63, s52
	v_lshl_add_u64 v[208:209], s[78:79], 0, v[130:131]
	s_mov_b32 m0, s76
	s_nop 0
	global_load_lds_dwordx4 v[208:209], off
	v_lshl_add_u64 v[212:213], v[208:209], 0, s[2:3]
	s_add_i32 m0, s76, 0x2000
	s_add_i32 s76, s64, s52
	global_load_lds_dwordx4 v[212:213], off
	v_lshl_add_u64 v[212:213], v[208:209], 0, s[8:9]
	s_mov_b32 m0, s76
	s_nop 0
	global_load_lds_dwordx4 v[212:213], off
	v_lshl_add_u64 v[212:213], v[208:209], 0, s[14:15]
	s_add_i32 m0, s76, 0x2000
	s_nop 0
	global_load_lds_dwordx4 v[212:213], off
	v_lshl_add_u64 v[212:213], s[74:75], 0, v[128:129]
	s_mov_b32 m0, s53
	v_lshl_add_u64 v[214:215], v[212:213], 0, s[2:3]
	global_load_lds_dwordx4 v[212:213], off
	s_mov_b32 m0, s54
	s_nop 0
	global_load_lds_dwordx4 v[214:215], off
	ds_read_b128 v[176:179], v143 offset:16384
	ds_read_b128 v[180:183], v143 offset:17408
	ds_read_b128 v[184:187], v143 offset:18432
	ds_read_b128 v[188:191], v143 offset:19456
	ds_read_b128 v[192:195], v143 offset:20480
	ds_read_b128 v[196:199], v143 offset:21504
	ds_read_b128 v[200:203], v143 offset:22528
	ds_read_b128 v[204:207], v143 offset:23552
	s_waitcnt vmcnt(8)
	s_waitcnt lgkmcnt(0)
	s_barrier
	s_waitcnt lgkmcnt(0)
	v_mfma_f32_16x16x32_bf16 v[60:63], v[144:147], v[176:179], v[60:63]
	v_mfma_f32_16x16x32_bf16 v[60:63], v[148:151], v[180:183], v[60:63]
	v_mfma_f32_16x16x32_bf16 v[56:59], v[156:159], v[180:183], v[56:59]
	v_mfma_f32_16x16x32_bf16 v[56:59], v[152:155], v[176:179], v[56:59]
	v_mfma_f32_16x16x32_bf16 v[44:47], v[160:163], v[176:179], v[44:47]
	v_mfma_f32_16x16x32_bf16 v[44:47], v[164:167], v[180:183], v[44:47]
	v_mfma_f32_16x16x32_bf16 v[40:43], v[172:175], v[180:183], v[40:43]
	v_mfma_f32_16x16x32_bf16 v[40:43], v[168:171], v[176:179], v[40:43]
	v_mfma_f32_16x16x32_bf16 v[24:27], v[168:171], v[184:187], v[24:27]
	v_mfma_f32_16x16x32_bf16 v[24:27], v[172:175], v[188:191], v[24:27]
	v_mfma_f32_16x16x32_bf16 v[28:31], v[164:167], v[188:191], v[28:31]
	v_mfma_f32_16x16x32_bf16 v[28:31], v[160:163], v[184:187], v[28:31]
	v_mfma_f32_16x16x32_bf16 v[48:51], v[152:155], v[184:187], v[48:51]
	v_mfma_f32_16x16x32_bf16 v[48:51], v[156:159], v[188:191], v[48:51]
	v_mfma_f32_16x16x32_bf16 v[52:55], v[148:151], v[188:191], v[52:55]
	v_mfma_f32_16x16x32_bf16 v[52:55], v[144:147], v[184:187], v[52:55]
	v_mfma_f32_16x16x32_bf16 v[36:39], v[144:147], v[192:195], v[36:39]
	v_mfma_f32_16x16x32_bf16 v[36:39], v[148:151], v[196:199], v[36:39]
	v_mfma_f32_16x16x32_bf16 v[32:35], v[156:159], v[196:199], v[32:35]
	v_mfma_f32_16x16x32_bf16 v[32:35], v[152:155], v[192:195], v[32:35]
	v_mfma_f32_16x16x32_bf16 v[12:15], v[160:163], v[192:195], v[12:15]
	v_mfma_f32_16x16x32_bf16 v[12:15], v[164:167], v[196:199], v[12:15]
	v_mfma_f32_16x16x32_bf16 v[8:11], v[172:175], v[196:199], v[8:11]
	v_mfma_f32_16x16x32_bf16 v[8:11], v[168:171], v[192:195], v[8:11]
	v_mfma_f32_16x16x32_bf16 v[0:3], v[168:171], v[200:203], v[0:3]
	v_mfma_f32_16x16x32_bf16 v[0:3], v[172:175], v[204:207], v[0:3]
	v_mfma_f32_16x16x32_bf16 v[4:7], v[164:167], v[204:207], v[4:7]
	v_mfma_f32_16x16x32_bf16 v[4:7], v[160:163], v[200:203], v[4:7]
	v_mfma_f32_16x16x32_bf16 v[16:19], v[152:155], v[200:203], v[16:19]
	v_mfma_f32_16x16x32_bf16 v[16:19], v[156:159], v[204:207], v[16:19]
	v_mfma_f32_16x16x32_bf16 v[20:23], v[148:151], v[204:207], v[20:23]
	v_mfma_f32_16x16x32_bf16 v[20:23], v[144:147], v[200:203], v[20:23]
	s_barrier
	s_add_i32 s74, 0, 0x18000
	s_add_i32 s75, 0, 0x1c000
	v_add_u32_e32 v156, s74, v140
	v_add_u32_e32 v172, s75, v140
	s_mov_b32 m0, s55
	v_lshl_add_u64 v[214:215], v[212:213], 0, s[8:9]
	global_load_lds_dwordx4 v[214:215], off
	v_lshl_add_u64 v[214:215], v[212:213], 0, s[14:15]
	s_mov_b32 m0, s56
	s_nop 0
	global_load_lds_dwordx4 v[214:215], off
	ds_read_b128 v[144:147], v156
	ds_read_b128 v[148:151], v156 offset:1024
	ds_read_b128 v[152:155], v156 offset:2048
	ds_read_b128 v[156:159], v156 offset:3072
	ds_read_b128 v[160:163], v172
	ds_read_b128 v[164:167], v172 offset:1024
	ds_read_b128 v[168:171], v172 offset:2048
	ds_read_b128 v[172:175], v172 offset:3072
	ds_read_b128 v[176:179], v143 offset:32768
	ds_read_b128 v[180:183], v143 offset:33792
	ds_read_b128 v[184:187], v143 offset:34816
	ds_read_b128 v[188:191], v143 offset:35840
	ds_read_b128 v[192:195], v143 offset:36864
	ds_read_b128 v[196:199], v143 offset:37888
	ds_read_b128 v[200:203], v143 offset:38912
	ds_read_b128 v[204:207], v143 offset:39936
	s_waitcnt vmcnt(8)
	s_waitcnt lgkmcnt(0)
	s_barrier
	s_waitcnt lgkmcnt(0)
	v_mfma_f32_16x16x32_bf16 v[124:127], v[144:147], v[176:179], v[124:127]
	v_mfma_f32_16x16x32_bf16 v[124:127], v[148:151], v[180:183], v[124:127]
	v_mfma_f32_16x16x32_bf16 v[120:123], v[156:159], v[180:183], v[120:123]
	v_mfma_f32_16x16x32_bf16 v[120:123], v[152:155], v[176:179], v[120:123]
	v_mfma_f32_16x16x32_bf16 v[108:111], v[160:163], v[176:179], v[108:111]
	v_mfma_f32_16x16x32_bf16 v[108:111], v[164:167], v[180:183], v[108:111]
	v_mfma_f32_16x16x32_bf16 v[104:107], v[172:175], v[180:183], v[104:107]
	v_mfma_f32_16x16x32_bf16 v[104:107], v[168:171], v[176:179], v[104:107]
	v_mfma_f32_16x16x32_bf16 v[88:91], v[168:171], v[184:187], v[88:91]
	v_mfma_f32_16x16x32_bf16 v[88:91], v[172:175], v[188:191], v[88:91]
	v_mfma_f32_16x16x32_bf16 v[92:95], v[164:167], v[188:191], v[92:95]
	v_mfma_f32_16x16x32_bf16 v[92:95], v[160:163], v[184:187], v[92:95]
	v_mfma_f32_16x16x32_bf16 v[112:115], v[152:155], v[184:187], v[112:115]
	v_mfma_f32_16x16x32_bf16 v[112:115], v[156:159], v[188:191], v[112:115]
	v_mfma_f32_16x16x32_bf16 v[116:119], v[148:151], v[188:191], v[116:119]
	v_mfma_f32_16x16x32_bf16 v[116:119], v[144:147], v[184:187], v[116:119]
	v_mfma_f32_16x16x32_bf16 v[100:103], v[144:147], v[192:195], v[100:103]
	v_mfma_f32_16x16x32_bf16 v[100:103], v[148:151], v[196:199], v[100:103]
	v_mfma_f32_16x16x32_bf16 v[96:99], v[156:159], v[196:199], v[96:99]
	v_mfma_f32_16x16x32_bf16 v[96:99], v[152:155], v[192:195], v[96:99]
	v_mfma_f32_16x16x32_bf16 v[76:79], v[160:163], v[192:195], v[76:79]
	v_mfma_f32_16x16x32_bf16 v[76:79], v[164:167], v[196:199], v[76:79]
	v_mfma_f32_16x16x32_bf16 v[72:75], v[172:175], v[196:199], v[72:75]
	v_mfma_f32_16x16x32_bf16 v[72:75], v[168:171], v[192:195], v[72:75]
	v_mfma_f32_16x16x32_bf16 v[64:67], v[168:171], v[200:203], v[64:67]
	v_mfma_f32_16x16x32_bf16 v[64:67], v[172:175], v[204:207], v[64:67]
	v_mfma_f32_16x16x32_bf16 v[68:71], v[164:167], v[204:207], v[68:71]
	v_mfma_f32_16x16x32_bf16 v[68:71], v[160:163], v[200:203], v[68:71]
	v_mfma_f32_16x16x32_bf16 v[80:83], v[152:155], v[200:203], v[80:83]
	v_mfma_f32_16x16x32_bf16 v[80:83], v[156:159], v[204:207], v[80:83]
	v_mfma_f32_16x16x32_bf16 v[84:87], v[148:151], v[204:207], v[84:87]
	v_mfma_f32_16x16x32_bf16 v[84:87], v[144:147], v[200:203], v[84:87]
	s_barrier
	s_add_i32 s74, s74, s52
	v_lshl_add_u64 v[214:215], v[208:209], 0, s[20:21]
	s_mov_b32 m0, s74
	s_nop 0
	global_load_lds_dwordx4 v[214:215], off
	v_lshl_add_u64 v[214:215], v[208:209], 0, s[22:23]
	s_add_i32 m0, s74, 0x2000
	s_add_i32 s74, s75, s52
	global_load_lds_dwordx4 v[214:215], off
	v_lshl_add_u64 v[214:215], v[208:209], 0, s[24:25]
	s_mov_b32 m0, s74
	v_lshl_add_u64 v[208:209], v[208:209], 0, s[26:27]
	global_load_lds_dwordx4 v[214:215], off
	s_add_i32 m0, s74, 0x2000
	s_nop 0
	global_load_lds_dwordx4 v[208:209], off
	v_lshl_add_u64 v[208:209], v[212:213], 0, s[20:21]
	s_mov_b32 m0, s58
	s_nop 0
	global_load_lds_dwordx4 v[208:209], off
	v_lshl_add_u64 v[208:209], v[212:213], 0, s[22:23]
	s_mov_b32 m0, s59
	s_nop 0
	global_load_lds_dwordx4 v[208:209], off
	ds_read_b128 v[176:179], v143 offset:49152
	ds_read_b128 v[180:183], v143 offset:50176
	ds_read_b128 v[184:187], v143 offset:51200
	ds_read_b128 v[188:191], v143 offset:52224
	ds_read_b128 v[192:195], v143 offset:53248
	ds_read_b128 v[196:199], v143 offset:54272
	ds_read_b128 v[200:203], v143 offset:55296
	ds_read_b128 v[204:207], v143 offset:56320
	s_waitcnt vmcnt(8)
	s_waitcnt lgkmcnt(0)
	s_barrier
	s_waitcnt lgkmcnt(0)
	v_mfma_f32_16x16x32_bf16 v[60:63], v[144:147], v[176:179], v[60:63]
	v_mfma_f32_16x16x32_bf16 v[60:63], v[148:151], v[180:183], v[60:63]
	v_mfma_f32_16x16x32_bf16 v[56:59], v[156:159], v[180:183], v[56:59]
	v_mfma_f32_16x16x32_bf16 v[56:59], v[152:155], v[176:179], v[56:59]
	v_mfma_f32_16x16x32_bf16 v[44:47], v[160:163], v[176:179], v[44:47]
	v_mfma_f32_16x16x32_bf16 v[44:47], v[164:167], v[180:183], v[44:47]
	v_mfma_f32_16x16x32_bf16 v[40:43], v[172:175], v[180:183], v[40:43]
	v_mfma_f32_16x16x32_bf16 v[40:43], v[168:171], v[176:179], v[40:43]
	v_mfma_f32_16x16x32_bf16 v[24:27], v[168:171], v[184:187], v[24:27]
	v_mfma_f32_16x16x32_bf16 v[24:27], v[172:175], v[188:191], v[24:27]
	v_mfma_f32_16x16x32_bf16 v[28:31], v[164:167], v[188:191], v[28:31]
	v_mfma_f32_16x16x32_bf16 v[28:31], v[160:163], v[184:187], v[28:31]
	v_mfma_f32_16x16x32_bf16 v[48:51], v[152:155], v[184:187], v[48:51]
	v_mfma_f32_16x16x32_bf16 v[48:51], v[156:159], v[188:191], v[48:51]
	v_mfma_f32_16x16x32_bf16 v[52:55], v[148:151], v[188:191], v[52:55]
	v_mfma_f32_16x16x32_bf16 v[52:55], v[144:147], v[184:187], v[52:55]
	v_mfma_f32_16x16x32_bf16 v[36:39], v[144:147], v[192:195], v[36:39]
	v_mfma_f32_16x16x32_bf16 v[36:39], v[148:151], v[196:199], v[36:39]
	v_mfma_f32_16x16x32_bf16 v[32:35], v[156:159], v[196:199], v[32:35]
	v_mfma_f32_16x16x32_bf16 v[32:35], v[152:155], v[192:195], v[32:35]
	v_mfma_f32_16x16x32_bf16 v[12:15], v[160:163], v[192:195], v[12:15]
	v_mfma_f32_16x16x32_bf16 v[12:15], v[164:167], v[196:199], v[12:15]
	v_mfma_f32_16x16x32_bf16 v[8:11], v[172:175], v[196:199], v[8:11]
	v_mfma_f32_16x16x32_bf16 v[8:11], v[168:171], v[192:195], v[8:11]
	v_mfma_f32_16x16x32_bf16 v[0:3], v[168:171], v[200:203], v[0:3]
	v_mfma_f32_16x16x32_bf16 v[0:3], v[172:175], v[204:207], v[0:3]
	v_mfma_f32_16x16x32_bf16 v[4:7], v[164:167], v[204:207], v[4:7]
	v_mfma_f32_16x16x32_bf16 v[4:7], v[160:163], v[200:203], v[4:7]
	v_mfma_f32_16x16x32_bf16 v[16:19], v[152:155], v[200:203], v[16:19]
	v_mfma_f32_16x16x32_bf16 v[16:19], v[156:159], v[204:207], v[16:19]
	v_mfma_f32_16x16x32_bf16 v[20:23], v[148:151], v[204:207], v[20:23]
	v_mfma_f32_16x16x32_bf16 v[20:23], v[144:147], v[200:203], v[20:23]
	s_barrier
	s_cmp_gt_u32 s73, 41
	s_cbranch_scc0 .LBB0_255
	s_and_b64 vcc, exec, s[28:29]
	s_cbranch_vccz .LBB0_258
	s_barrier

.LBB0_386:
	s_add_i32 s70, s70, 2
	s_mov_b32 s42, s70
	s_ashr_i32 s43, s42, 31
	s_lshl_b64 s[72:73], s[42:43], 7
	s_add_u32 s43, s72, 0x100
	s_addc_u32 s71, s73, 0
	s_add_u32 s79, s8, s43
	s_addc_u32 s80, s9, s71
	s_add_u32 s82, s2, s43
	s_addc_u32 s71, s3, s71
	s_add_i32 s83, 0, 0x10000
	s_cmp_eq_u32 s42, 14
	s_cselect_b32 s43, s1, s80
	s_cselect_b32 s42, s57, s79
	s_cselect_b32 s81, s68, s71
	s_cselect_b32 s80, s69, s82
	s_add_i32 s71, 0, 0x14000
	v_add_u32_e32 v140, s83, v220
	v_add_u32_e32 v156, s71, v220
	s_add_u32 s72, s8, s72
	s_addc_u32 s73, s9, s73
	v_lshl_add_u64 v[222:223], s[72:73], 0, v[182:183]
	v_lshl_add_u64 v[224:225], v[222:223], 0, s[14:15]
	s_add_i32 m0, s39, 0xc000
	s_nop 0
	global_load_lds_dwordx4 v[224:225], off
	v_lshl_add_u64 v[222:223], v[222:223], 0, s[16:17]
	s_add_i32 m0, s39, 0xe000
	s_nop 0
	global_load_lds_dwordx4 v[222:223], off
	ds_read_b128 v[128:131], v140
	ds_read_b128 v[132:135], v140 offset:1024
	ds_read_b128 v[136:139], v140 offset:2048
	ds_read_b128 v[140:143], v140 offset:3072
	ds_read_b128 v[144:147], v156
	ds_read_b128 v[148:151], v156 offset:1024
	ds_read_b128 v[152:155], v156 offset:2048
	ds_read_b128 v[156:159], v156 offset:3072
	ds_read_b128 v[160:163], v221
	ds_read_b128 v[164:167], v221 offset:1024
	ds_read_b128 v[186:189], v221 offset:2048
	ds_read_b128 v[190:193], v221 offset:3072
	ds_read_b128 v[194:197], v221 offset:4096
	ds_read_b128 v[198:201], v221 offset:5120
	ds_read_b128 v[202:205], v221 offset:6144
	ds_read_b128 v[206:209], v221 offset:7168
	s_waitcnt vmcnt(8)
	s_waitcnt lgkmcnt(0)
	s_barrier
	s_waitcnt lgkmcnt(0)
	v_mfma_f32_16x16x32_bf16 v[124:127], v[128:131], v[160:163], v[124:127]
	v_mfma_f32_16x16x32_bf16 v[124:127], v[132:135], v[164:167], v[124:127]
	v_mfma_f32_16x16x32_bf16 v[120:123], v[140:143], v[164:167], v[120:123]
	v_mfma_f32_16x16x32_bf16 v[120:123], v[136:139], v[160:163], v[120:123]
	v_mfma_f32_16x16x32_bf16 v[116:119], v[144:147], v[160:163], v[116:119]
	v_mfma_f32_16x16x32_bf16 v[116:119], v[148:151], v[164:167], v[116:119]
	v_mfma_f32_16x16x32_bf16 v[108:111], v[156:159], v[164:167], v[108:111]
	v_mfma_f32_16x16x32_bf16 v[108:111], v[152:155], v[160:163], v[108:111]
	v_mfma_f32_16x16x32_bf16 v[92:95], v[152:155], v[186:189], v[92:95]
	v_mfma_f32_16x16x32_bf16 v[92:95], v[156:159], v[190:193], v[92:95]
	v_mfma_f32_16x16x32_bf16 v[100:103], v[148:151], v[190:193], v[100:103]
	v_mfma_f32_16x16x32_bf16 v[100:103], v[144:147], v[186:189], v[100:103]
	v_mfma_f32_16x16x32_bf16 v[104:107], v[136:139], v[186:189], v[104:107]
	v_mfma_f32_16x16x32_bf16 v[104:107], v[140:143], v[190:193], v[104:107]
	v_mfma_f32_16x16x32_bf16 v[112:115], v[132:135], v[190:193], v[112:115]
	v_mfma_f32_16x16x32_bf16 v[112:115], v[128:131], v[186:189], v[112:115]
	v_mfma_f32_16x16x32_bf16 v[96:99], v[128:131], v[194:197], v[96:99]
	v_mfma_f32_16x16x32_bf16 v[96:99], v[132:135], v[198:201], v[96:99]
	v_mfma_f32_16x16x32_bf16 v[88:91], v[140:143], v[198:201], v[88:91]
	v_mfma_f32_16x16x32_bf16 v[88:91], v[136:139], v[194:197], v[88:91]
	v_mfma_f32_16x16x32_bf16 v[84:87], v[144:147], v[194:197], v[84:87]
	v_mfma_f32_16x16x32_bf16 v[84:87], v[148:151], v[198:201], v[84:87]
	v_mfma_f32_16x16x32_bf16 v[76:79], v[156:159], v[198:201], v[76:79]
	v_mfma_f32_16x16x32_bf16 v[76:79], v[152:155], v[194:197], v[76:79]
	v_mfma_f32_16x16x32_bf16 v[64:67], v[152:155], v[202:205], v[64:67]
	v_mfma_f32_16x16x32_bf16 v[64:67], v[156:159], v[206:209], v[64:67]
	v_mfma_f32_16x16x32_bf16 v[68:71], v[148:151], v[206:209], v[68:71]
	v_mfma_f32_16x16x32_bf16 v[68:71], v[144:147], v[202:205], v[68:71]
	v_mfma_f32_16x16x32_bf16 v[72:75], v[136:139], v[202:205], v[72:75]
	v_mfma_f32_16x16x32_bf16 v[72:75], v[140:143], v[206:209], v[72:75]
	v_mfma_f32_16x16x32_bf16 v[80:83], v[132:135], v[206:209], v[80:83]
	v_mfma_f32_16x16x32_bf16 v[80:83], v[128:131], v[202:205], v[80:83]
	s_barrier
	s_add_i32 s72, s83, s74
	v_lshl_add_u64 v[222:223], s[80:81], 0, v[184:185]
	s_mov_b32 m0, s72
	s_nop 0
	global_load_lds_dwordx4 v[222:223], off
	v_lshl_add_u64 v[224:225], v[222:223], 0, s[40:41]
	s_add_i32 m0, s72, 0x2000
	s_add_i32 s71, s71, s74
	global_load_lds_dwordx4 v[224:225], off
	v_lshl_add_u64 v[224:225], v[222:223], 0, s[4:5]
	s_mov_b32 m0, s71
	s_nop 0
	global_load_lds_dwordx4 v[224:225], off
	v_lshl_add_u64 v[224:225], v[222:223], 0, s[6:7]
	s_add_i32 m0, s71, 0x2000
	s_nop 0
	global_load_lds_dwordx4 v[224:225], off
	v_lshl_add_u64 v[224:225], s[42:43], 0, v[182:183]
	s_mov_b32 m0, s39
	v_lshl_add_u64 v[226:227], v[224:225], 0, s[40:41]
	global_load_lds_dwordx4 v[224:225], off
	s_mov_b32 m0, s75
	s_nop 0
	global_load_lds_dwordx4 v[226:227], off
	ds_read_b128 v[160:163], v221 offset:16384
	ds_read_b128 v[164:167], v221 offset:17408
	ds_read_b128 v[186:189], v221 offset:18432
	ds_read_b128 v[190:193], v221 offset:19456
	ds_read_b128 v[194:197], v221 offset:20480
	ds_read_b128 v[198:201], v221 offset:21504
	ds_read_b128 v[202:205], v221 offset:22528
	ds_read_b128 v[206:209], v221 offset:23552
	s_waitcnt vmcnt(8)
	s_waitcnt lgkmcnt(0)
	s_barrier
	s_waitcnt lgkmcnt(0)
	v_mfma_f32_16x16x32_bf16 v[60:63], v[128:131], v[160:163], v[60:63]
	v_mfma_f32_16x16x32_bf16 v[60:63], v[132:135], v[164:167], v[60:63]
	v_mfma_f32_16x16x32_bf16 v[56:59], v[140:143], v[164:167], v[56:59]
	v_mfma_f32_16x16x32_bf16 v[56:59], v[136:139], v[160:163], v[56:59]
	v_mfma_f32_16x16x32_bf16 v[52:55], v[144:147], v[160:163], v[52:55]
	v_mfma_f32_16x16x32_bf16 v[52:55], v[148:151], v[164:167], v[52:55]
	v_mfma_f32_16x16x32_bf16 v[44:47], v[156:159], v[164:167], v[44:47]
	v_mfma_f32_16x16x32_bf16 v[44:47], v[152:155], v[160:163], v[44:47]
	v_mfma_f32_16x16x32_bf16 v[28:31], v[152:155], v[186:189], v[28:31]
	v_mfma_f32_16x16x32_bf16 v[28:31], v[156:159], v[190:193], v[28:31]
	v_mfma_f32_16x16x32_bf16 v[36:39], v[148:151], v[190:193], v[36:39]
	v_mfma_f32_16x16x32_bf16 v[36:39], v[144:147], v[186:189], v[36:39]
	v_mfma_f32_16x16x32_bf16 v[40:43], v[136:139], v[186:189], v[40:43]
	v_mfma_f32_16x16x32_bf16 v[40:43], v[140:143], v[190:193], v[40:43]
	v_mfma_f32_16x16x32_bf16 v[48:51], v[132:135], v[190:193], v[48:51]
	v_mfma_f32_16x16x32_bf16 v[48:51], v[128:131], v[186:189], v[48:51]
	v_mfma_f32_16x16x32_bf16 v[32:35], v[128:131], v[194:197], v[32:35]
	v_mfma_f32_16x16x32_bf16 v[32:35], v[132:135], v[198:201], v[32:35]
	v_mfma_f32_16x16x32_bf16 v[24:27], v[140:143], v[198:201], v[24:27]
	v_mfma_f32_16x16x32_bf16 v[24:27], v[136:139], v[194:197], v[24:27]
	v_mfma_f32_16x16x32_bf16 v[20:23], v[144:147], v[194:197], v[20:23]
	v_mfma_f32_16x16x32_bf16 v[20:23], v[148:151], v[198:201], v[20:23]
	v_mfma_f32_16x16x32_bf16 v[12:15], v[156:159], v[198:201], v[12:15]
	v_mfma_f32_16x16x32_bf16 v[12:15], v[152:155], v[194:197], v[12:15]
	v_mfma_f32_16x16x32_bf16 v[0:3], v[152:155], v[202:205], v[0:3]
	v_mfma_f32_16x16x32_bf16 v[0:3], v[156:159], v[206:209], v[0:3]
	v_mfma_f32_16x16x32_bf16 v[4:7], v[148:151], v[206:209], v[4:7]
	v_mfma_f32_16x16x32_bf16 v[4:7], v[144:147], v[202:205], v[4:7]
	v_mfma_f32_16x16x32_bf16 v[8:11], v[136:139], v[202:205], v[8:11]
	v_mfma_f32_16x16x32_bf16 v[8:11], v[140:143], v[206:209], v[8:11]
	v_mfma_f32_16x16x32_bf16 v[16:19], v[132:135], v[206:209], v[16:19]
	v_mfma_f32_16x16x32_bf16 v[16:19], v[128:131], v[202:205], v[16:19]
	s_barrier
	s_add_i32 s42, 0, 0x18000
	s_add_i32 s43, 0, 0x1c000
	v_add_u32_e32 v140, s42, v220
	v_add_u32_e32 v156, s43, v220
	s_mov_b32 m0, s30
	v_lshl_add_u64 v[226:227], v[224:225], 0, s[4:5]
	global_load_lds_dwordx4 v[226:227], off
	v_lshl_add_u64 v[226:227], v[224:225], 0, s[6:7]
	s_mov_b32 m0, s31
	s_nop 0
	global_load_lds_dwordx4 v[226:227], off
	ds_read_b128 v[128:131], v140
	ds_read_b128 v[132:135], v140 offset:1024
	ds_read_b128 v[136:139], v140 offset:2048
	ds_read_b128 v[140:143], v140 offset:3072
	ds_read_b128 v[144:147], v156
	ds_read_b128 v[148:151], v156 offset:1024
	ds_read_b128 v[152:155], v156 offset:2048
	ds_read_b128 v[156:159], v156 offset:3072
	ds_read_b128 v[160:163], v221 offset:32768
	ds_read_b128 v[164:167], v221 offset:33792
	ds_read_b128 v[186:189], v221 offset:34816
	ds_read_b128 v[190:193], v221 offset:35840
	ds_read_b128 v[194:197], v221 offset:36864
	ds_read_b128 v[198:201], v221 offset:37888
	ds_read_b128 v[202:205], v221 offset:38912
	ds_read_b128 v[206:209], v221 offset:39936
	s_waitcnt vmcnt(8)
	s_waitcnt lgkmcnt(0)
	s_barrier
	s_waitcnt lgkmcnt(0)
	v_mfma_f32_16x16x32_bf16 v[124:127], v[128:131], v[160:163], v[124:127]
	v_mfma_f32_16x16x32_bf16 v[124:127], v[132:135], v[164:167], v[124:127]
	v_mfma_f32_16x16x32_bf16 v[120:123], v[140:143], v[164:167], v[120:123]
	v_mfma_f32_16x16x32_bf16 v[120:123], v[136:139], v[160:163], v[120:123]
	v_mfma_f32_16x16x32_bf16 v[116:119], v[144:147], v[160:163], v[116:119]
	v_mfma_f32_16x16x32_bf16 v[116:119], v[148:151], v[164:167], v[116:119]
	v_mfma_f32_16x16x32_bf16 v[108:111], v[156:159], v[164:167], v[108:111]
	v_mfma_f32_16x16x32_bf16 v[108:111], v[152:155], v[160:163], v[108:111]
	v_mfma_f32_16x16x32_bf16 v[92:95], v[152:155], v[186:189], v[92:95]
	v_mfma_f32_16x16x32_bf16 v[92:95], v[156:159], v[190:193], v[92:95]
	v_mfma_f32_16x16x32_bf16 v[100:103], v[148:151], v[190:193], v[100:103]
	v_mfma_f32_16x16x32_bf16 v[100:103], v[144:147], v[186:189], v[100:103]
	v_mfma_f32_16x16x32_bf16 v[104:107], v[136:139], v[186:189], v[104:107]
	v_mfma_f32_16x16x32_bf16 v[104:107], v[140:143], v[190:193], v[104:107]
	v_mfma_f32_16x16x32_bf16 v[112:115], v[132:135], v[190:193], v[112:115]
	v_mfma_f32_16x16x32_bf16 v[112:115], v[128:131], v[186:189], v[112:115]
	v_mfma_f32_16x16x32_bf16 v[96:99], v[128:131], v[194:197], v[96:99]
	v_mfma_f32_16x16x32_bf16 v[96:99], v[132:135], v[198:201], v[96:99]
	v_mfma_f32_16x16x32_bf16 v[88:91], v[140:143], v[198:201], v[88:91]
	v_mfma_f32_16x16x32_bf16 v[88:91], v[136:139], v[194:197], v[88:91]
	v_mfma_f32_16x16x32_bf16 v[84:87], v[144:147], v[194:197], v[84:87]
	v_mfma_f32_16x16x32_bf16 v[84:87], v[148:151], v[198:201], v[84:87]
	v_mfma_f32_16x16x32_bf16 v[76:79], v[156:159], v[198:201], v[76:79]
	v_mfma_f32_16x16x32_bf16 v[76:79], v[152:155], v[194:197], v[76:79]
	v_mfma_f32_16x16x32_bf16 v[64:67], v[152:155], v[202:205], v[64:67]
	v_mfma_f32_16x16x32_bf16 v[64:67], v[156:159], v[206:209], v[64:67]
	v_mfma_f32_16x16x32_bf16 v[68:71], v[148:151], v[206:209], v[68:71]
	v_mfma_f32_16x16x32_bf16 v[68:71], v[144:147], v[202:205], v[68:71]
	v_mfma_f32_16x16x32_bf16 v[72:75], v[136:139], v[202:205], v[72:75]
	v_mfma_f32_16x16x32_bf16 v[72:75], v[140:143], v[206:209], v[72:75]
	v_mfma_f32_16x16x32_bf16 v[80:83], v[132:135], v[206:209], v[80:83]
	v_mfma_f32_16x16x32_bf16 v[80:83], v[128:131], v[202:205], v[80:83]
	s_barrier
	s_add_i32 s42, s42, s74
	v_lshl_add_u64 v[226:227], v[222:223], 0, s[10:11]
	s_mov_b32 m0, s42
	s_nop 0
	global_load_lds_dwordx4 v[226:227], off
	v_lshl_add_u64 v[226:227], v[222:223], 0, s[12:13]
	s_add_i32 m0, s42, 0x2000
	s_add_i32 s42, s43, s74
	global_load_lds_dwordx4 v[226:227], off
	v_lshl_add_u64 v[226:227], v[222:223], 0, s[14:15]
	s_mov_b32 m0, s42
	v_lshl_add_u64 v[222:223], v[222:223], 0, s[16:17]
	global_load_lds_dwordx4 v[226:227], off
	s_add_i32 m0, s42, 0x2000
	s_nop 0
	global_load_lds_dwordx4 v[222:223], off
	v_lshl_add_u64 v[222:223], v[224:225], 0, s[10:11]
	s_mov_b32 m0, s26
	s_nop 0
	global_load_lds_dwordx4 v[222:223], off
	v_lshl_add_u64 v[222:223], v[224:225], 0, s[12:13]
	s_mov_b32 m0, s27
	s_nop 0
	global_load_lds_dwordx4 v[222:223], off
	ds_read_b128 v[160:163], v221 offset:49152
	ds_read_b128 v[164:167], v221 offset:50176
	ds_read_b128 v[186:189], v221 offset:51200
	ds_read_b128 v[190:193], v221 offset:52224
	ds_read_b128 v[194:197], v221 offset:53248
	ds_read_b128 v[198:201], v221 offset:54272
	ds_read_b128 v[202:205], v221 offset:55296
	ds_read_b128 v[206:209], v221 offset:56320
	s_waitcnt vmcnt(8)
	s_waitcnt lgkmcnt(0)
	s_barrier
	s_waitcnt lgkmcnt(0)
	v_mfma_f32_16x16x32_bf16 v[60:63], v[128:131], v[160:163], v[60:63]
	v_mfma_f32_16x16x32_bf16 v[60:63], v[132:135], v[164:167], v[60:63]
	v_mfma_f32_16x16x32_bf16 v[56:59], v[140:143], v[164:167], v[56:59]
	v_mfma_f32_16x16x32_bf16 v[56:59], v[136:139], v[160:163], v[56:59]
	v_mfma_f32_16x16x32_bf16 v[52:55], v[144:147], v[160:163], v[52:55]
	v_mfma_f32_16x16x32_bf16 v[52:55], v[148:151], v[164:167], v[52:55]
	v_mfma_f32_16x16x32_bf16 v[44:47], v[156:159], v[164:167], v[44:47]
	v_mfma_f32_16x16x32_bf16 v[44:47], v[152:155], v[160:163], v[44:47]
	v_mfma_f32_16x16x32_bf16 v[28:31], v[152:155], v[186:189], v[28:31]
	v_mfma_f32_16x16x32_bf16 v[28:31], v[156:159], v[190:193], v[28:31]
	v_mfma_f32_16x16x32_bf16 v[36:39], v[148:151], v[190:193], v[36:39]
	v_mfma_f32_16x16x32_bf16 v[36:39], v[144:147], v[186:189], v[36:39]
	v_mfma_f32_16x16x32_bf16 v[40:43], v[136:139], v[186:189], v[40:43]
	v_mfma_f32_16x16x32_bf16 v[40:43], v[140:143], v[190:193], v[40:43]
	v_mfma_f32_16x16x32_bf16 v[48:51], v[132:135], v[190:193], v[48:51]
	v_mfma_f32_16x16x32_bf16 v[48:51], v[128:131], v[186:189], v[48:51]
	v_mfma_f32_16x16x32_bf16 v[32:35], v[128:131], v[194:197], v[32:35]
	v_mfma_f32_16x16x32_bf16 v[32:35], v[132:135], v[198:201], v[32:35]
	v_mfma_f32_16x16x32_bf16 v[24:27], v[140:143], v[198:201], v[24:27]
	v_mfma_f32_16x16x32_bf16 v[24:27], v[136:139], v[194:197], v[24:27]
	v_mfma_f32_16x16x32_bf16 v[20:23], v[144:147], v[194:197], v[20:23]
	v_mfma_f32_16x16x32_bf16 v[20:23], v[148:151], v[198:201], v[20:23]
	v_mfma_f32_16x16x32_bf16 v[12:15], v[156:159], v[198:201], v[12:15]
	v_mfma_f32_16x16x32_bf16 v[12:15], v[152:155], v[194:197], v[12:15]
	v_mfma_f32_16x16x32_bf16 v[0:3], v[152:155], v[202:205], v[0:3]
	v_mfma_f32_16x16x32_bf16 v[0:3], v[156:159], v[206:209], v[0:3]
	v_mfma_f32_16x16x32_bf16 v[4:7], v[148:151], v[206:209], v[4:7]
	v_mfma_f32_16x16x32_bf16 v[4:7], v[144:147], v[202:205], v[4:7]
	v_mfma_f32_16x16x32_bf16 v[8:11], v[136:139], v[202:205], v[8:11]
	v_mfma_f32_16x16x32_bf16 v[8:11], v[140:143], v[206:209], v[8:11]
	v_mfma_f32_16x16x32_bf16 v[16:19], v[132:135], v[206:209], v[16:19]
	v_mfma_f32_16x16x32_bf16 v[16:19], v[128:131], v[202:205], v[16:19]
	s_barrier
	s_cmp_gt_u32 s70, 13
	s_cbranch_scc0 .LBB0_386
	s_and_b64 vcc, exec, s[58:59]
	s_cbranch_vccz .LBB0_389
	s_barrier

.LBB0_760:
	s_add_i32 s78, s78, 2
	s_mov_b32 s50, s78
	s_ashr_i32 s51, s50, 31
	s_lshl_b64 s[80:81], s[50:51], 7
	s_add_u32 s51, s80, 0x100
	s_addc_u32 s79, s81, 0
	s_add_u32 s82, s48, s51
	s_addc_u32 s83, s49, s79
	s_add_u32 s84, s8, s51
	s_addc_u32 s79, s9, s79
	s_add_i32 s85, 0, 0x10000
	s_cmp_eq_u32 s50, 14
	s_cselect_b32 s51, s35, s83
	s_cselect_b32 s50, s76, s82
	s_cselect_b32 s83, s31, s79
	s_cselect_b32 s82, s77, s84
	s_add_i32 s79, 0, 0x14000
	s_add_u32 s80, s48, s80
	s_addc_u32 s81, s49, s81
	v_lshl_add_u64 v[134:135], s[80:81], 0, v[128:129]
	v_lshl_add_u64 v[224:225], v[134:135], 0, s[14:15]
	s_add_i32 m0, s62, 0xc000
	s_nop 0
	global_load_lds_dwordx4 v[224:225], off
	v_lshl_add_u64 v[134:135], v[134:135], 0, s[16:17]
	s_add_i32 m0, s62, 0xe000
	s_nop 0
	global_load_lds_dwordx4 v[134:135], off
	v_add_u32_e32 v134, s85, v137
	ds_read_b128 v[130:133], v134
	ds_read_b128 v[140:143], v134 offset:1024
	ds_read_b128 v[144:147], v134 offset:2048
	ds_read_b128 v[148:151], v134 offset:3072
	v_add_u32_e32 v134, s79, v137
	ds_read_b128 v[152:155], v134
	ds_read_b128 v[156:159], v134 offset:1024
	ds_read_b128 v[160:163], v134 offset:2048
	ds_read_b128 v[164:167], v134 offset:3072
	ds_read_b128 v[182:185], v138
	ds_read_b128 v[186:189], v138 offset:1024
	ds_read_b128 v[190:193], v138 offset:2048
	ds_read_b128 v[194:197], v138 offset:3072
	ds_read_b128 v[198:201], v138 offset:4096
	ds_read_b128 v[202:205], v138 offset:5120
	ds_read_b128 v[206:209], v138 offset:6144
	ds_read_b128 v[220:223], v138 offset:7168
	s_nop 0
	s_waitcnt vmcnt(8)
	s_waitcnt lgkmcnt(0)
	s_barrier
	s_waitcnt lgkmcnt(0)
	v_mfma_f32_16x16x32_bf16 v[124:127], v[130:133], v[182:185], v[124:127]
	v_mfma_f32_16x16x32_bf16 v[124:127], v[140:143], v[186:189], v[124:127]
	v_mfma_f32_16x16x32_bf16 v[120:123], v[148:151], v[186:189], v[120:123]
	v_mfma_f32_16x16x32_bf16 v[120:123], v[144:147], v[182:185], v[120:123]
	v_mfma_f32_16x16x32_bf16 v[116:119], v[152:155], v[182:185], v[116:119]
	v_mfma_f32_16x16x32_bf16 v[116:119], v[156:159], v[186:189], v[116:119]
	v_mfma_f32_16x16x32_bf16 v[112:115], v[164:167], v[186:189], v[112:115]
	v_mfma_f32_16x16x32_bf16 v[112:115], v[160:163], v[182:185], v[112:115]
	v_mfma_f32_16x16x32_bf16 v[96:99], v[160:163], v[190:193], v[96:99]
	v_mfma_f32_16x16x32_bf16 v[96:99], v[164:167], v[194:197], v[96:99]
	v_mfma_f32_16x16x32_bf16 v[100:103], v[156:159], v[194:197], v[100:103]
	v_mfma_f32_16x16x32_bf16 v[100:103], v[152:155], v[190:193], v[100:103]
	v_mfma_f32_16x16x32_bf16 v[104:107], v[144:147], v[190:193], v[104:107]
	v_mfma_f32_16x16x32_bf16 v[104:107], v[148:151], v[194:197], v[104:107]
	v_mfma_f32_16x16x32_bf16 v[108:111], v[140:143], v[194:197], v[108:111]
	v_mfma_f32_16x16x32_bf16 v[108:111], v[130:133], v[190:193], v[108:111]
	v_mfma_f32_16x16x32_bf16 v[92:95], v[130:133], v[198:201], v[92:95]
	v_mfma_f32_16x16x32_bf16 v[92:95], v[140:143], v[202:205], v[92:95]
	v_mfma_f32_16x16x32_bf16 v[88:91], v[148:151], v[202:205], v[88:91]
	v_mfma_f32_16x16x32_bf16 v[88:91], v[144:147], v[198:201], v[88:91]
	v_mfma_f32_16x16x32_bf16 v[84:87], v[152:155], v[198:201], v[84:87]
	v_mfma_f32_16x16x32_bf16 v[84:87], v[156:159], v[202:205], v[84:87]
	v_mfma_f32_16x16x32_bf16 v[80:83], v[164:167], v[202:205], v[80:83]
	v_mfma_f32_16x16x32_bf16 v[80:83], v[160:163], v[198:201], v[80:83]
	v_mfma_f32_16x16x32_bf16 v[64:67], v[160:163], v[206:209], v[64:67]
	v_mfma_f32_16x16x32_bf16 v[64:67], v[164:167], v[220:223], v[64:67]
	v_mfma_f32_16x16x32_bf16 v[68:71], v[156:159], v[220:223], v[68:71]
	v_mfma_f32_16x16x32_bf16 v[68:71], v[152:155], v[206:209], v[68:71]
	v_mfma_f32_16x16x32_bf16 v[72:75], v[144:147], v[206:209], v[72:75]
	v_mfma_f32_16x16x32_bf16 v[72:75], v[148:151], v[220:223], v[72:75]
	v_mfma_f32_16x16x32_bf16 v[76:79], v[140:143], v[220:223], v[76:79]
	v_mfma_f32_16x16x32_bf16 v[76:79], v[130:133], v[206:209], v[76:79]
	s_barrier
	s_add_i32 s80, s85, s59
	v_lshl_add_u64 v[134:135], s[82:83], 0, v[172:173]
	s_mov_b32 m0, s80
	s_nop 0
	global_load_lds_dwordx4 v[134:135], off
	v_lshl_add_u64 v[224:225], v[134:135], 0, s[40:41]
	s_add_i32 m0, s80, 0x2000
	s_add_i32 s79, s79, s59
	global_load_lds_dwordx4 v[224:225], off
	v_lshl_add_u64 v[224:225], v[134:135], 0, s[4:5]
	s_mov_b32 m0, s79
	s_nop 0
	global_load_lds_dwordx4 v[224:225], off
	v_lshl_add_u64 v[224:225], v[134:135], 0, s[6:7]
	s_add_i32 m0, s79, 0x2000
	s_nop 0
	global_load_lds_dwordx4 v[224:225], off
	v_lshl_add_u64 v[224:225], s[50:51], 0, v[128:129]
	s_mov_b32 m0, s62
	v_lshl_add_u64 v[226:227], v[224:225], 0, s[40:41]
	global_load_lds_dwordx4 v[224:225], off
	s_mov_b32 m0, s63
	s_nop 0
	global_load_lds_dwordx4 v[226:227], off
	ds_read_b128 v[182:185], v138 offset:16384
	ds_read_b128 v[186:189], v138 offset:17408
	ds_read_b128 v[190:193], v138 offset:18432
	ds_read_b128 v[194:197], v138 offset:19456
	ds_read_b128 v[198:201], v138 offset:20480
	ds_read_b128 v[202:205], v138 offset:21504
	ds_read_b128 v[206:209], v138 offset:22528
	ds_read_b128 v[220:223], v138 offset:23552
	s_waitcnt vmcnt(8)
	s_waitcnt lgkmcnt(0)
	s_barrier
	s_waitcnt lgkmcnt(0)
	v_mfma_f32_16x16x32_bf16 v[60:63], v[130:133], v[182:185], v[60:63]
	v_mfma_f32_16x16x32_bf16 v[60:63], v[140:143], v[186:189], v[60:63]
	v_mfma_f32_16x16x32_bf16 v[56:59], v[148:151], v[186:189], v[56:59]
	v_mfma_f32_16x16x32_bf16 v[56:59], v[144:147], v[182:185], v[56:59]
	v_mfma_f32_16x16x32_bf16 v[52:55], v[152:155], v[182:185], v[52:55]
	v_mfma_f32_16x16x32_bf16 v[52:55], v[156:159], v[186:189], v[52:55]
	v_mfma_f32_16x16x32_bf16 v[48:51], v[164:167], v[186:189], v[48:51]
	v_mfma_f32_16x16x32_bf16 v[48:51], v[160:163], v[182:185], v[48:51]
	v_mfma_f32_16x16x32_bf16 v[32:35], v[160:163], v[190:193], v[32:35]
	v_mfma_f32_16x16x32_bf16 v[32:35], v[164:167], v[194:197], v[32:35]
	v_mfma_f32_16x16x32_bf16 v[36:39], v[156:159], v[194:197], v[36:39]
	v_mfma_f32_16x16x32_bf16 v[36:39], v[152:155], v[190:193], v[36:39]
	v_mfma_f32_16x16x32_bf16 v[40:43], v[144:147], v[190:193], v[40:43]
	v_mfma_f32_16x16x32_bf16 v[40:43], v[148:151], v[194:197], v[40:43]
	v_mfma_f32_16x16x32_bf16 v[44:47], v[140:143], v[194:197], v[44:47]
	v_mfma_f32_16x16x32_bf16 v[44:47], v[130:133], v[190:193], v[44:47]
	v_mfma_f32_16x16x32_bf16 v[28:31], v[130:133], v[198:201], v[28:31]
	v_mfma_f32_16x16x32_bf16 v[28:31], v[140:143], v[202:205], v[28:31]
	v_mfma_f32_16x16x32_bf16 v[24:27], v[148:151], v[202:205], v[24:27]
	v_mfma_f32_16x16x32_bf16 v[24:27], v[144:147], v[198:201], v[24:27]
	v_mfma_f32_16x16x32_bf16 v[20:23], v[152:155], v[198:201], v[20:23]
	v_mfma_f32_16x16x32_bf16 v[20:23], v[156:159], v[202:205], v[20:23]
	v_mfma_f32_16x16x32_bf16 v[16:19], v[164:167], v[202:205], v[16:19]
	v_mfma_f32_16x16x32_bf16 v[16:19], v[160:163], v[198:201], v[16:19]
	v_mfma_f32_16x16x32_bf16 v[0:3], v[160:163], v[206:209], v[0:3]
	v_mfma_f32_16x16x32_bf16 v[0:3], v[164:167], v[220:223], v[0:3]
	v_mfma_f32_16x16x32_bf16 v[4:7], v[156:159], v[220:223], v[4:7]
	v_mfma_f32_16x16x32_bf16 v[4:7], v[152:155], v[206:209], v[4:7]
	v_mfma_f32_16x16x32_bf16 v[8:11], v[144:147], v[206:209], v[8:11]
	v_mfma_f32_16x16x32_bf16 v[8:11], v[148:151], v[220:223], v[8:11]
	v_mfma_f32_16x16x32_bf16 v[12:15], v[140:143], v[220:223], v[12:15]
	v_mfma_f32_16x16x32_bf16 v[12:15], v[130:133], v[206:209], v[12:15]
	s_barrier
	s_mov_b32 m0, s68
	v_lshl_add_u64 v[226:227], v[224:225], 0, s[4:5]
	global_load_lds_dwordx4 v[226:227], off
	v_lshl_add_u64 v[226:227], v[224:225], 0, s[6:7]
	s_mov_b32 m0, s69
	s_nop 0
	global_load_lds_dwordx4 v[226:227], off
	s_add_i32 s50, 0, 0x18000
	v_add_u32_e32 v139, s50, v137
	s_add_i32 s51, 0, 0x1c000
	ds_read_b128 v[130:133], v139
	ds_read_b128 v[140:143], v139 offset:1024
	ds_read_b128 v[144:147], v139 offset:2048
	ds_read_b128 v[148:151], v139 offset:3072
	v_add_u32_e32 v139, s51, v137
	ds_read_b128 v[152:155], v139
	ds_read_b128 v[156:159], v139 offset:1024
	ds_read_b128 v[160:163], v139 offset:2048
	ds_read_b128 v[164:167], v139 offset:3072
	ds_read_b128 v[182:185], v138 offset:32768
	ds_read_b128 v[186:189], v138 offset:33792
	ds_read_b128 v[190:193], v138 offset:34816
	ds_read_b128 v[194:197], v138 offset:35840
	ds_read_b128 v[198:201], v138 offset:36864
	ds_read_b128 v[202:205], v138 offset:37888
	ds_read_b128 v[206:209], v138 offset:38912
	ds_read_b128 v[220:223], v138 offset:39936
	s_nop 0
	s_waitcnt vmcnt(8)
	s_waitcnt lgkmcnt(0)
	s_barrier
	s_waitcnt lgkmcnt(0)
	v_mfma_f32_16x16x32_bf16 v[124:127], v[130:133], v[182:185], v[124:127]
	v_mfma_f32_16x16x32_bf16 v[124:127], v[140:143], v[186:189], v[124:127]
	v_mfma_f32_16x16x32_bf16 v[120:123], v[148:151], v[186:189], v[120:123]
	v_mfma_f32_16x16x32_bf16 v[120:123], v[144:147], v[182:185], v[120:123]
	v_mfma_f32_16x16x32_bf16 v[116:119], v[152:155], v[182:185], v[116:119]
	v_mfma_f32_16x16x32_bf16 v[116:119], v[156:159], v[186:189], v[116:119]
	v_mfma_f32_16x16x32_bf16 v[112:115], v[164:167], v[186:189], v[112:115]
	v_mfma_f32_16x16x32_bf16 v[112:115], v[160:163], v[182:185], v[112:115]
	v_mfma_f32_16x16x32_bf16 v[96:99], v[160:163], v[190:193], v[96:99]
	v_mfma_f32_16x16x32_bf16 v[96:99], v[164:167], v[194:197], v[96:99]
	v_mfma_f32_16x16x32_bf16 v[100:103], v[156:159], v[194:197], v[100:103]
	v_mfma_f32_16x16x32_bf16 v[100:103], v[152:155], v[190:193], v[100:103]
	v_mfma_f32_16x16x32_bf16 v[104:107], v[144:147], v[190:193], v[104:107]
	v_mfma_f32_16x16x32_bf16 v[104:107], v[148:151], v[194:197], v[104:107]
	v_mfma_f32_16x16x32_bf16 v[108:111], v[140:143], v[194:197], v[108:111]
	v_mfma_f32_16x16x32_bf16 v[108:111], v[130:133], v[190:193], v[108:111]
	v_mfma_f32_16x16x32_bf16 v[92:95], v[130:133], v[198:201], v[92:95]
	v_mfma_f32_16x16x32_bf16 v[92:95], v[140:143], v[202:205], v[92:95]
	v_mfma_f32_16x16x32_bf16 v[88:91], v[148:151], v[202:205], v[88:91]
	v_mfma_f32_16x16x32_bf16 v[88:91], v[144:147], v[198:201], v[88:91]
	v_mfma_f32_16x16x32_bf16 v[84:87], v[152:155], v[198:201], v[84:87]
	v_mfma_f32_16x16x32_bf16 v[84:87], v[156:159], v[202:205], v[84:87]
	v_mfma_f32_16x16x32_bf16 v[80:83], v[164:167], v[202:205], v[80:83]
	v_mfma_f32_16x16x32_bf16 v[80:83], v[160:163], v[198:201], v[80:83]
	v_mfma_f32_16x16x32_bf16 v[64:67], v[160:163], v[206:209], v[64:67]
	v_mfma_f32_16x16x32_bf16 v[64:67], v[164:167], v[220:223], v[64:67]
	v_mfma_f32_16x16x32_bf16 v[68:71], v[156:159], v[220:223], v[68:71]
	v_mfma_f32_16x16x32_bf16 v[68:71], v[152:155], v[206:209], v[68:71]
	v_mfma_f32_16x16x32_bf16 v[72:75], v[144:147], v[206:209], v[72:75]
	v_mfma_f32_16x16x32_bf16 v[72:75], v[148:151], v[220:223], v[72:75]
	v_mfma_f32_16x16x32_bf16 v[76:79], v[140:143], v[220:223], v[76:79]
	v_mfma_f32_16x16x32_bf16 v[76:79], v[130:133], v[206:209], v[76:79]
	s_barrier
	s_add_i32 s50, s50, s59
	v_lshl_add_u64 v[226:227], v[134:135], 0, s[10:11]
	s_mov_b32 m0, s50
	s_nop 0
	global_load_lds_dwordx4 v[226:227], off
	v_lshl_add_u64 v[226:227], v[134:135], 0, s[12:13]
	s_add_i32 m0, s50, 0x2000
	s_add_i32 s50, s51, s59
	global_load_lds_dwordx4 v[226:227], off
	v_lshl_add_u64 v[226:227], v[134:135], 0, s[14:15]
	s_mov_b32 m0, s50
	v_lshl_add_u64 v[134:135], v[134:135], 0, s[16:17]
	global_load_lds_dwordx4 v[226:227], off
	s_add_i32 m0, s50, 0x2000
	s_nop 0
	global_load_lds_dwordx4 v[134:135], off
	v_lshl_add_u64 v[134:135], v[224:225], 0, s[10:11]
	s_mov_b32 m0, s72
	s_nop 0
	global_load_lds_dwordx4 v[134:135], off
	v_lshl_add_u64 v[134:135], v[224:225], 0, s[12:13]
	s_mov_b32 m0, s73
	s_nop 0
	global_load_lds_dwordx4 v[134:135], off
	ds_read_b128 v[182:185], v138 offset:49152
	ds_read_b128 v[186:189], v138 offset:50176
	ds_read_b128 v[190:193], v138 offset:51200
	ds_read_b128 v[194:197], v138 offset:52224
	ds_read_b128 v[198:201], v138 offset:53248
	ds_read_b128 v[202:205], v138 offset:54272
	ds_read_b128 v[206:209], v138 offset:55296
	ds_read_b128 v[220:223], v138 offset:56320
	s_waitcnt vmcnt(8)
	s_waitcnt lgkmcnt(0)
	s_barrier
	s_waitcnt lgkmcnt(0)
	v_mfma_f32_16x16x32_bf16 v[60:63], v[130:133], v[182:185], v[60:63]
	v_mfma_f32_16x16x32_bf16 v[60:63], v[140:143], v[186:189], v[60:63]
	v_mfma_f32_16x16x32_bf16 v[56:59], v[148:151], v[186:189], v[56:59]
	v_mfma_f32_16x16x32_bf16 v[56:59], v[144:147], v[182:185], v[56:59]
	v_mfma_f32_16x16x32_bf16 v[52:55], v[152:155], v[182:185], v[52:55]
	v_mfma_f32_16x16x32_bf16 v[52:55], v[156:159], v[186:189], v[52:55]
	v_mfma_f32_16x16x32_bf16 v[48:51], v[164:167], v[186:189], v[48:51]
	v_mfma_f32_16x16x32_bf16 v[48:51], v[160:163], v[182:185], v[48:51]
	v_mfma_f32_16x16x32_bf16 v[32:35], v[160:163], v[190:193], v[32:35]
	v_mfma_f32_16x16x32_bf16 v[32:35], v[164:167], v[194:197], v[32:35]
	v_mfma_f32_16x16x32_bf16 v[36:39], v[156:159], v[194:197], v[36:39]
	v_mfma_f32_16x16x32_bf16 v[36:39], v[152:155], v[190:193], v[36:39]
	v_mfma_f32_16x16x32_bf16 v[40:43], v[144:147], v[190:193], v[40:43]
	v_mfma_f32_16x16x32_bf16 v[40:43], v[148:151], v[194:197], v[40:43]
	v_mfma_f32_16x16x32_bf16 v[44:47], v[140:143], v[194:197], v[44:47]
	v_mfma_f32_16x16x32_bf16 v[44:47], v[130:133], v[190:193], v[44:47]
	v_mfma_f32_16x16x32_bf16 v[28:31], v[130:133], v[198:201], v[28:31]
	v_mfma_f32_16x16x32_bf16 v[28:31], v[140:143], v[202:205], v[28:31]
	v_mfma_f32_16x16x32_bf16 v[24:27], v[148:151], v[202:205], v[24:27]
	v_mfma_f32_16x16x32_bf16 v[24:27], v[144:147], v[198:201], v[24:27]
	v_mfma_f32_16x16x32_bf16 v[20:23], v[152:155], v[198:201], v[20:23]
	v_mfma_f32_16x16x32_bf16 v[20:23], v[156:159], v[202:205], v[20:23]
	v_mfma_f32_16x16x32_bf16 v[16:19], v[164:167], v[202:205], v[16:19]
	v_mfma_f32_16x16x32_bf16 v[16:19], v[160:163], v[198:201], v[16:19]
	v_mfma_f32_16x16x32_bf16 v[0:3], v[160:163], v[206:209], v[0:3]
	v_mfma_f32_16x16x32_bf16 v[0:3], v[164:167], v[220:223], v[0:3]
	v_mfma_f32_16x16x32_bf16 v[4:7], v[156:159], v[220:223], v[4:7]
	v_mfma_f32_16x16x32_bf16 v[4:7], v[152:155], v[206:209], v[4:7]
	v_mfma_f32_16x16x32_bf16 v[8:11], v[144:147], v[206:209], v[8:11]
	v_mfma_f32_16x16x32_bf16 v[8:11], v[148:151], v[220:223], v[8:11]
	v_mfma_f32_16x16x32_bf16 v[12:15], v[140:143], v[220:223], v[12:15]
	v_mfma_f32_16x16x32_bf16 v[12:15], v[130:133], v[206:209], v[12:15]
	s_barrier
	s_cmp_gt_u32 s78, 13
	s_cbranch_scc0 .LBB0_760
	s_and_b64 vcc, exec, s[28:29]
	s_cbranch_vccz .LBB0_763
	s_barrier

.LBB0_784:
	s_add_i32 s80, s80, 2
	s_mov_b32 s48, s80
	s_ashr_i32 s49, s48, 31
	s_lshl_b64 s[82:83], s[48:49], 7
	s_add_u32 s49, s82, 0x100
	s_addc_u32 s81, s83, 0
	s_add_u32 s84, s42, s49
	s_addc_u32 s85, s43, s81
	s_add_u32 s86, s8, s49
	s_addc_u32 s81, s9, s81
	s_add_i32 s87, 0, 0x10000
	s_cmp_eq_u32 s48, 14
	s_cselect_b32 s49, s39, s85
	s_cselect_b32 s48, s72, s84
	s_cselect_b32 s85, s35, s81
	s_cselect_b32 s84, s73, s86
	s_add_i32 s81, 0, 0x14000
	s_add_u32 s82, s42, s82
	s_addc_u32 s83, s43, s83
	v_lshl_add_u64 v[134:135], s[82:83], 0, v[128:129]
	v_lshl_add_u64 v[224:225], v[134:135], 0, s[14:15]
	s_add_i32 m0, s74, 0xc000
	s_nop 0
	global_load_lds_dwordx4 v[224:225], off
	v_lshl_add_u64 v[134:135], v[134:135], 0, s[16:17]
	s_add_i32 m0, s74, 0xe000
	s_nop 0
	global_load_lds_dwordx4 v[134:135], off
	v_add_u32_e32 v134, s87, v137
	ds_read_b128 v[130:133], v134
	ds_read_b128 v[140:143], v134 offset:1024
	ds_read_b128 v[144:147], v134 offset:2048
	ds_read_b128 v[148:151], v134 offset:3072
	v_add_u32_e32 v134, s81, v137
	ds_read_b128 v[152:155], v134
	ds_read_b128 v[156:159], v134 offset:1024
	ds_read_b128 v[160:163], v134 offset:2048
	ds_read_b128 v[164:167], v134 offset:3072
	ds_read_b128 v[182:185], v138
	ds_read_b128 v[186:189], v138 offset:1024
	ds_read_b128 v[190:193], v138 offset:2048
	ds_read_b128 v[194:197], v138 offset:3072
	ds_read_b128 v[198:201], v138 offset:4096
	ds_read_b128 v[202:205], v138 offset:5120
	ds_read_b128 v[206:209], v138 offset:6144
	ds_read_b128 v[220:223], v138 offset:7168
	s_nop 0
	s_waitcnt vmcnt(8)
	s_waitcnt lgkmcnt(0)
	s_barrier
	s_waitcnt lgkmcnt(0)
	v_mfma_f32_16x16x32_bf16 v[124:127], v[130:133], v[182:185], v[124:127]
	v_mfma_f32_16x16x32_bf16 v[124:127], v[140:143], v[186:189], v[124:127]
	v_mfma_f32_16x16x32_bf16 v[120:123], v[148:151], v[186:189], v[120:123]
	v_mfma_f32_16x16x32_bf16 v[120:123], v[144:147], v[182:185], v[120:123]
	v_mfma_f32_16x16x32_bf16 v[116:119], v[152:155], v[182:185], v[116:119]
	v_mfma_f32_16x16x32_bf16 v[116:119], v[156:159], v[186:189], v[116:119]
	v_mfma_f32_16x16x32_bf16 v[112:115], v[164:167], v[186:189], v[112:115]
	v_mfma_f32_16x16x32_bf16 v[112:115], v[160:163], v[182:185], v[112:115]
	v_mfma_f32_16x16x32_bf16 v[96:99], v[160:163], v[190:193], v[96:99]
	v_mfma_f32_16x16x32_bf16 v[96:99], v[164:167], v[194:197], v[96:99]
	v_mfma_f32_16x16x32_bf16 v[100:103], v[156:159], v[194:197], v[100:103]
	v_mfma_f32_16x16x32_bf16 v[100:103], v[152:155], v[190:193], v[100:103]
	v_mfma_f32_16x16x32_bf16 v[104:107], v[144:147], v[190:193], v[104:107]
	v_mfma_f32_16x16x32_bf16 v[104:107], v[148:151], v[194:197], v[104:107]
	v_mfma_f32_16x16x32_bf16 v[108:111], v[140:143], v[194:197], v[108:111]
	v_mfma_f32_16x16x32_bf16 v[108:111], v[130:133], v[190:193], v[108:111]
	v_mfma_f32_16x16x32_bf16 v[92:95], v[130:133], v[198:201], v[92:95]
	v_mfma_f32_16x16x32_bf16 v[92:95], v[140:143], v[202:205], v[92:95]
	v_mfma_f32_16x16x32_bf16 v[88:91], v[148:151], v[202:205], v[88:91]
	v_mfma_f32_16x16x32_bf16 v[88:91], v[144:147], v[198:201], v[88:91]
	v_mfma_f32_16x16x32_bf16 v[84:87], v[152:155], v[198:201], v[84:87]
	v_mfma_f32_16x16x32_bf16 v[84:87], v[156:159], v[202:205], v[84:87]
	v_mfma_f32_16x16x32_bf16 v[80:83], v[164:167], v[202:205], v[80:83]
	v_mfma_f32_16x16x32_bf16 v[80:83], v[160:163], v[198:201], v[80:83]
	v_mfma_f32_16x16x32_bf16 v[64:67], v[160:163], v[206:209], v[64:67]
	v_mfma_f32_16x16x32_bf16 v[64:67], v[164:167], v[220:223], v[64:67]
	v_mfma_f32_16x16x32_bf16 v[68:71], v[156:159], v[220:223], v[68:71]
	v_mfma_f32_16x16x32_bf16 v[68:71], v[152:155], v[206:209], v[68:71]
	v_mfma_f32_16x16x32_bf16 v[72:75], v[144:147], v[206:209], v[72:75]
	v_mfma_f32_16x16x32_bf16 v[72:75], v[148:151], v[220:223], v[72:75]
	v_mfma_f32_16x16x32_bf16 v[76:79], v[140:143], v[220:223], v[76:79]
	v_mfma_f32_16x16x32_bf16 v[76:79], v[130:133], v[206:209], v[76:79]
	s_barrier
	s_add_i32 s82, s87, s63
	v_lshl_add_u64 v[134:135], s[84:85], 0, v[172:173]
	s_mov_b32 m0, s82
	s_nop 0
	global_load_lds_dwordx4 v[134:135], off
	v_lshl_add_u64 v[224:225], v[134:135], 0, s[40:41]
	s_add_i32 m0, s82, 0x2000
	s_add_i32 s81, s81, s63
	global_load_lds_dwordx4 v[224:225], off
	v_lshl_add_u64 v[224:225], v[134:135], 0, s[4:5]
	s_mov_b32 m0, s81
	s_nop 0
	global_load_lds_dwordx4 v[224:225], off
	v_lshl_add_u64 v[224:225], v[134:135], 0, s[6:7]
	s_add_i32 m0, s81, 0x2000
	s_nop 0
	global_load_lds_dwordx4 v[224:225], off
	v_lshl_add_u64 v[224:225], s[48:49], 0, v[128:129]
	s_mov_b32 m0, s74
	v_lshl_add_u64 v[226:227], v[224:225], 0, s[40:41]
	global_load_lds_dwordx4 v[224:225], off
	s_mov_b32 m0, s75
	s_nop 0
	global_load_lds_dwordx4 v[226:227], off
	ds_read_b128 v[182:185], v138 offset:16384
	ds_read_b128 v[186:189], v138 offset:17408
	ds_read_b128 v[190:193], v138 offset:18432
	ds_read_b128 v[194:197], v138 offset:19456
	ds_read_b128 v[198:201], v138 offset:20480
	ds_read_b128 v[202:205], v138 offset:21504
	ds_read_b128 v[206:209], v138 offset:22528
	ds_read_b128 v[220:223], v138 offset:23552
	s_waitcnt vmcnt(8)
	s_waitcnt lgkmcnt(0)
	s_barrier
	s_waitcnt lgkmcnt(0)
	v_mfma_f32_16x16x32_bf16 v[60:63], v[130:133], v[182:185], v[60:63]
	v_mfma_f32_16x16x32_bf16 v[60:63], v[140:143], v[186:189], v[60:63]
	v_mfma_f32_16x16x32_bf16 v[56:59], v[148:151], v[186:189], v[56:59]
	v_mfma_f32_16x16x32_bf16 v[56:59], v[144:147], v[182:185], v[56:59]
	v_mfma_f32_16x16x32_bf16 v[52:55], v[152:155], v[182:185], v[52:55]
	v_mfma_f32_16x16x32_bf16 v[52:55], v[156:159], v[186:189], v[52:55]
	v_mfma_f32_16x16x32_bf16 v[48:51], v[164:167], v[186:189], v[48:51]
	v_mfma_f32_16x16x32_bf16 v[48:51], v[160:163], v[182:185], v[48:51]
	v_mfma_f32_16x16x32_bf16 v[32:35], v[160:163], v[190:193], v[32:35]
	v_mfma_f32_16x16x32_bf16 v[32:35], v[164:167], v[194:197], v[32:35]
	v_mfma_f32_16x16x32_bf16 v[36:39], v[156:159], v[194:197], v[36:39]
	v_mfma_f32_16x16x32_bf16 v[36:39], v[152:155], v[190:193], v[36:39]
	v_mfma_f32_16x16x32_bf16 v[40:43], v[144:147], v[190:193], v[40:43]
	v_mfma_f32_16x16x32_bf16 v[40:43], v[148:151], v[194:197], v[40:43]
	v_mfma_f32_16x16x32_bf16 v[44:47], v[140:143], v[194:197], v[44:47]
	v_mfma_f32_16x16x32_bf16 v[44:47], v[130:133], v[190:193], v[44:47]
	v_mfma_f32_16x16x32_bf16 v[28:31], v[130:133], v[198:201], v[28:31]
	v_mfma_f32_16x16x32_bf16 v[28:31], v[140:143], v[202:205], v[28:31]
	v_mfma_f32_16x16x32_bf16 v[24:27], v[148:151], v[202:205], v[24:27]
	v_mfma_f32_16x16x32_bf16 v[24:27], v[144:147], v[198:201], v[24:27]
	v_mfma_f32_16x16x32_bf16 v[20:23], v[152:155], v[198:201], v[20:23]
	v_mfma_f32_16x16x32_bf16 v[20:23], v[156:159], v[202:205], v[20:23]
	v_mfma_f32_16x16x32_bf16 v[16:19], v[164:167], v[202:205], v[16:19]
	v_mfma_f32_16x16x32_bf16 v[16:19], v[160:163], v[198:201], v[16:19]
	v_mfma_f32_16x16x32_bf16 v[0:3], v[160:163], v[206:209], v[0:3]
	v_mfma_f32_16x16x32_bf16 v[0:3], v[164:167], v[220:223], v[0:3]
	v_mfma_f32_16x16x32_bf16 v[4:7], v[156:159], v[220:223], v[4:7]
	v_mfma_f32_16x16x32_bf16 v[4:7], v[152:155], v[206:209], v[4:7]
	v_mfma_f32_16x16x32_bf16 v[8:11], v[144:147], v[206:209], v[8:11]
	v_mfma_f32_16x16x32_bf16 v[8:11], v[148:151], v[220:223], v[8:11]
	v_mfma_f32_16x16x32_bf16 v[12:15], v[140:143], v[220:223], v[12:15]
	v_mfma_f32_16x16x32_bf16 v[12:15], v[130:133], v[206:209], v[12:15]
	s_barrier
	s_mov_b32 m0, s76
	v_lshl_add_u64 v[226:227], v[224:225], 0, s[4:5]
	global_load_lds_dwordx4 v[226:227], off
	v_lshl_add_u64 v[226:227], v[224:225], 0, s[6:7]
	s_mov_b32 m0, s77
	s_nop 0
	global_load_lds_dwordx4 v[226:227], off
	s_add_i32 s48, 0, 0x18000
	v_add_u32_e32 v139, s48, v137
	s_add_i32 s49, 0, 0x1c000
	ds_read_b128 v[130:133], v139
	ds_read_b128 v[140:143], v139 offset:1024
	ds_read_b128 v[144:147], v139 offset:2048
	ds_read_b128 v[148:151], v139 offset:3072
	v_add_u32_e32 v139, s49, v137
	ds_read_b128 v[152:155], v139
	ds_read_b128 v[156:159], v139 offset:1024
	ds_read_b128 v[160:163], v139 offset:2048
	ds_read_b128 v[164:167], v139 offset:3072
	ds_read_b128 v[182:185], v138 offset:32768
	ds_read_b128 v[186:189], v138 offset:33792
	ds_read_b128 v[190:193], v138 offset:34816
	ds_read_b128 v[194:197], v138 offset:35840
	ds_read_b128 v[198:201], v138 offset:36864
	ds_read_b128 v[202:205], v138 offset:37888
	ds_read_b128 v[206:209], v138 offset:38912
	ds_read_b128 v[220:223], v138 offset:39936
	s_nop 0
	s_waitcnt vmcnt(8)
	s_waitcnt lgkmcnt(0)
	s_barrier
	s_waitcnt lgkmcnt(0)
	v_mfma_f32_16x16x32_bf16 v[124:127], v[130:133], v[182:185], v[124:127]
	v_mfma_f32_16x16x32_bf16 v[124:127], v[140:143], v[186:189], v[124:127]
	v_mfma_f32_16x16x32_bf16 v[120:123], v[148:151], v[186:189], v[120:123]
	v_mfma_f32_16x16x32_bf16 v[120:123], v[144:147], v[182:185], v[120:123]
	v_mfma_f32_16x16x32_bf16 v[116:119], v[152:155], v[182:185], v[116:119]
	v_mfma_f32_16x16x32_bf16 v[116:119], v[156:159], v[186:189], v[116:119]
	v_mfma_f32_16x16x32_bf16 v[112:115], v[164:167], v[186:189], v[112:115]
	v_mfma_f32_16x16x32_bf16 v[112:115], v[160:163], v[182:185], v[112:115]
	v_mfma_f32_16x16x32_bf16 v[96:99], v[160:163], v[190:193], v[96:99]
	v_mfma_f32_16x16x32_bf16 v[96:99], v[164:167], v[194:197], v[96:99]
	v_mfma_f32_16x16x32_bf16 v[100:103], v[156:159], v[194:197], v[100:103]
	v_mfma_f32_16x16x32_bf16 v[100:103], v[152:155], v[190:193], v[100:103]
	v_mfma_f32_16x16x32_bf16 v[104:107], v[144:147], v[190:193], v[104:107]
	v_mfma_f32_16x16x32_bf16 v[104:107], v[148:151], v[194:197], v[104:107]
	v_mfma_f32_16x16x32_bf16 v[108:111], v[140:143], v[194:197], v[108:111]
	v_mfma_f32_16x16x32_bf16 v[108:111], v[130:133], v[190:193], v[108:111]
	v_mfma_f32_16x16x32_bf16 v[92:95], v[130:133], v[198:201], v[92:95]
	v_mfma_f32_16x16x32_bf16 v[92:95], v[140:143], v[202:205], v[92:95]
	v_mfma_f32_16x16x32_bf16 v[88:91], v[148:151], v[202:205], v[88:91]
	v_mfma_f32_16x16x32_bf16 v[88:91], v[144:147], v[198:201], v[88:91]
	v_mfma_f32_16x16x32_bf16 v[84:87], v[152:155], v[198:201], v[84:87]
	v_mfma_f32_16x16x32_bf16 v[84:87], v[156:159], v[202:205], v[84:87]
	v_mfma_f32_16x16x32_bf16 v[80:83], v[164:167], v[202:205], v[80:83]
	v_mfma_f32_16x16x32_bf16 v[80:83], v[160:163], v[198:201], v[80:83]
	v_mfma_f32_16x16x32_bf16 v[64:67], v[160:163], v[206:209], v[64:67]
	v_mfma_f32_16x16x32_bf16 v[64:67], v[164:167], v[220:223], v[64:67]
	v_mfma_f32_16x16x32_bf16 v[68:71], v[156:159], v[220:223], v[68:71]
	v_mfma_f32_16x16x32_bf16 v[68:71], v[152:155], v[206:209], v[68:71]
	v_mfma_f32_16x16x32_bf16 v[72:75], v[144:147], v[206:209], v[72:75]
	v_mfma_f32_16x16x32_bf16 v[72:75], v[148:151], v[220:223], v[72:75]
	v_mfma_f32_16x16x32_bf16 v[76:79], v[140:143], v[220:223], v[76:79]
	v_mfma_f32_16x16x32_bf16 v[76:79], v[130:133], v[206:209], v[76:79]
	s_barrier
	s_add_i32 s48, s48, s63
	v_lshl_add_u64 v[226:227], v[134:135], 0, s[10:11]
	s_mov_b32 m0, s48
	s_nop 0
	global_load_lds_dwordx4 v[226:227], off
	v_lshl_add_u64 v[226:227], v[134:135], 0, s[12:13]
	s_add_i32 m0, s48, 0x2000
	s_add_i32 s48, s49, s63
	global_load_lds_dwordx4 v[226:227], off
	v_lshl_add_u64 v[226:227], v[134:135], 0, s[14:15]
	s_mov_b32 m0, s48
	v_lshl_add_u64 v[134:135], v[134:135], 0, s[16:17]
	global_load_lds_dwordx4 v[226:227], off
	s_add_i32 m0, s48, 0x2000
	s_nop 0
	global_load_lds_dwordx4 v[134:135], off
	v_lshl_add_u64 v[134:135], v[224:225], 0, s[10:11]
	s_mov_b32 m0, s68
	s_nop 0
	global_load_lds_dwordx4 v[134:135], off
	v_lshl_add_u64 v[134:135], v[224:225], 0, s[12:13]
	s_mov_b32 m0, s69
	s_nop 0
	global_load_lds_dwordx4 v[134:135], off
	ds_read_b128 v[182:185], v138 offset:49152
	ds_read_b128 v[186:189], v138 offset:50176
	ds_read_b128 v[190:193], v138 offset:51200
	ds_read_b128 v[194:197], v138 offset:52224
	ds_read_b128 v[198:201], v138 offset:53248
	ds_read_b128 v[202:205], v138 offset:54272
	ds_read_b128 v[206:209], v138 offset:55296
	ds_read_b128 v[220:223], v138 offset:56320
	s_waitcnt vmcnt(8)
	s_waitcnt lgkmcnt(0)
	s_barrier
	s_waitcnt lgkmcnt(0)
	v_mfma_f32_16x16x32_bf16 v[60:63], v[130:133], v[182:185], v[60:63]
	v_mfma_f32_16x16x32_bf16 v[60:63], v[140:143], v[186:189], v[60:63]
	v_mfma_f32_16x16x32_bf16 v[56:59], v[148:151], v[186:189], v[56:59]
	v_mfma_f32_16x16x32_bf16 v[56:59], v[144:147], v[182:185], v[56:59]
	v_mfma_f32_16x16x32_bf16 v[52:55], v[152:155], v[182:185], v[52:55]
	v_mfma_f32_16x16x32_bf16 v[52:55], v[156:159], v[186:189], v[52:55]
	v_mfma_f32_16x16x32_bf16 v[48:51], v[164:167], v[186:189], v[48:51]
	v_mfma_f32_16x16x32_bf16 v[48:51], v[160:163], v[182:185], v[48:51]
	v_mfma_f32_16x16x32_bf16 v[32:35], v[160:163], v[190:193], v[32:35]
	v_mfma_f32_16x16x32_bf16 v[32:35], v[164:167], v[194:197], v[32:35]
	v_mfma_f32_16x16x32_bf16 v[36:39], v[156:159], v[194:197], v[36:39]
	v_mfma_f32_16x16x32_bf16 v[36:39], v[152:155], v[190:193], v[36:39]
	v_mfma_f32_16x16x32_bf16 v[40:43], v[144:147], v[190:193], v[40:43]
	v_mfma_f32_16x16x32_bf16 v[40:43], v[148:151], v[194:197], v[40:43]
	v_mfma_f32_16x16x32_bf16 v[44:47], v[140:143], v[194:197], v[44:47]
	v_mfma_f32_16x16x32_bf16 v[44:47], v[130:133], v[190:193], v[44:47]
	v_mfma_f32_16x16x32_bf16 v[28:31], v[130:133], v[198:201], v[28:31]
	v_mfma_f32_16x16x32_bf16 v[28:31], v[140:143], v[202:205], v[28:31]
	v_mfma_f32_16x16x32_bf16 v[24:27], v[148:151], v[202:205], v[24:27]
	v_mfma_f32_16x16x32_bf16 v[24:27], v[144:147], v[198:201], v[24:27]
	v_mfma_f32_16x16x32_bf16 v[20:23], v[152:155], v[198:201], v[20:23]
	v_mfma_f32_16x16x32_bf16 v[20:23], v[156:159], v[202:205], v[20:23]
	v_mfma_f32_16x16x32_bf16 v[16:19], v[164:167], v[202:205], v[16:19]
	v_mfma_f32_16x16x32_bf16 v[16:19], v[160:163], v[198:201], v[16:19]
	v_mfma_f32_16x16x32_bf16 v[0:3], v[160:163], v[206:209], v[0:3]
	v_mfma_f32_16x16x32_bf16 v[0:3], v[164:167], v[220:223], v[0:3]
	v_mfma_f32_16x16x32_bf16 v[4:7], v[156:159], v[220:223], v[4:7]
	v_mfma_f32_16x16x32_bf16 v[4:7], v[152:155], v[206:209], v[4:7]
	v_mfma_f32_16x16x32_bf16 v[8:11], v[144:147], v[206:209], v[8:11]
	v_mfma_f32_16x16x32_bf16 v[8:11], v[148:151], v[220:223], v[8:11]
	v_mfma_f32_16x16x32_bf16 v[12:15], v[140:143], v[220:223], v[12:15]
	v_mfma_f32_16x16x32_bf16 v[12:15], v[130:133], v[206:209], v[12:15]
	s_barrier
	s_cmp_gt_u32 s80, 13
	s_cbranch_scc0 .LBB0_784
	s_and_b64 vcc, exec, s[30:31]
	s_cbranch_vccz .LBB0_787
	s_barrier

.LBB0_856:
	s_add_i32 s78, s78, 2
	s_mov_b32 s50, s78
	s_ashr_i32 s51, s50, 31
	s_lshl_b64 s[80:81], s[50:51], 7
	v_lshl_add_u64 v[224:225], v[130:131], 0, s[80:81]
	v_lshl_add_u64 v[226:227], v[224:225], 0, s[10:11]
	s_add_i32 m0, s62, 0xc000
	s_nop 0
	global_load_lds_dwordx4 v[226:227], off
	v_lshl_add_u64 v[224:225], v[224:225], 0, s[12:13]
	s_add_i32 m0, s62, 0xe000
	s_nop 0
	global_load_lds_dwordx4 v[224:225], off
	s_add_u32 s51, s80, 0x100
	s_addc_u32 s79, s81, 0
	s_add_u32 s82, s30, s51
	s_addc_u32 s83, s31, s79
	s_add_u32 s84, s28, s51
	s_addc_u32 s79, s29, s79
	s_add_i32 s85, 0, 0x10000
	s_cmp_eq_u32 s50, 14
	s_cselect_b32 s51, s39, s83
	s_cselect_b32 s50, s76, s82
	v_add_u32_e32 v135, s85, v133
	s_cselect_b32 s83, s35, s79
	s_cselect_b32 s82, s77, s84
	s_add_i32 s79, 0, 0x14000
	ds_read_b128 v[136:139], v135
	ds_read_b128 v[140:143], v135 offset:1024
	ds_read_b128 v[144:147], v135 offset:2048
	ds_read_b128 v[148:151], v135 offset:3072
	v_add_u32_e32 v135, s79, v133
	ds_read_b128 v[152:155], v135
	ds_read_b128 v[156:159], v135 offset:1024
	ds_read_b128 v[160:163], v135 offset:2048
	ds_read_b128 v[164:167], v135 offset:3072
	ds_read_b128 v[182:185], v134
	ds_read_b128 v[186:189], v134 offset:1024
	ds_read_b128 v[190:193], v134 offset:2048
	ds_read_b128 v[194:197], v134 offset:3072
	ds_read_b128 v[198:201], v134 offset:4096
	ds_read_b128 v[202:205], v134 offset:5120
	ds_read_b128 v[206:209], v134 offset:6144
	ds_read_b128 v[220:223], v134 offset:7168
	s_nop 0
	s_waitcnt vmcnt(8)
	s_waitcnt lgkmcnt(0)
	s_barrier
	s_waitcnt lgkmcnt(0)
	v_mfma_f32_16x16x32_bf16 v[124:127], v[136:139], v[182:185], v[124:127]
	v_mfma_f32_16x16x32_bf16 v[124:127], v[140:143], v[186:189], v[124:127]
	v_mfma_f32_16x16x32_bf16 v[120:123], v[148:151], v[186:189], v[120:123]
	v_mfma_f32_16x16x32_bf16 v[120:123], v[144:147], v[182:185], v[120:123]
	v_mfma_f32_16x16x32_bf16 v[108:111], v[152:155], v[182:185], v[108:111]
	v_mfma_f32_16x16x32_bf16 v[108:111], v[156:159], v[186:189], v[108:111]
	v_mfma_f32_16x16x32_bf16 v[104:107], v[164:167], v[186:189], v[104:107]
	v_mfma_f32_16x16x32_bf16 v[104:107], v[160:163], v[182:185], v[104:107]
	v_mfma_f32_16x16x32_bf16 v[88:91], v[160:163], v[190:193], v[88:91]
	v_mfma_f32_16x16x32_bf16 v[88:91], v[164:167], v[194:197], v[88:91]
	v_mfma_f32_16x16x32_bf16 v[92:95], v[156:159], v[194:197], v[92:95]
	v_mfma_f32_16x16x32_bf16 v[92:95], v[152:155], v[190:193], v[92:95]
	v_mfma_f32_16x16x32_bf16 v[112:115], v[144:147], v[190:193], v[112:115]
	v_mfma_f32_16x16x32_bf16 v[112:115], v[148:151], v[194:197], v[112:115]
	v_mfma_f32_16x16x32_bf16 v[116:119], v[140:143], v[194:197], v[116:119]
	v_mfma_f32_16x16x32_bf16 v[116:119], v[136:139], v[190:193], v[116:119]
	v_mfma_f32_16x16x32_bf16 v[100:103], v[136:139], v[198:201], v[100:103]
	v_mfma_f32_16x16x32_bf16 v[100:103], v[140:143], v[202:205], v[100:103]
	v_mfma_f32_16x16x32_bf16 v[96:99], v[148:151], v[202:205], v[96:99]
	v_mfma_f32_16x16x32_bf16 v[96:99], v[144:147], v[198:201], v[96:99]
	v_mfma_f32_16x16x32_bf16 v[76:79], v[152:155], v[198:201], v[76:79]
	v_mfma_f32_16x16x32_bf16 v[76:79], v[156:159], v[202:205], v[76:79]
	v_mfma_f32_16x16x32_bf16 v[72:75], v[164:167], v[202:205], v[72:75]
	v_mfma_f32_16x16x32_bf16 v[72:75], v[160:163], v[198:201], v[72:75]
	v_mfma_f32_16x16x32_bf16 v[64:67], v[160:163], v[206:209], v[64:67]
	v_mfma_f32_16x16x32_bf16 v[64:67], v[164:167], v[220:223], v[64:67]
	v_mfma_f32_16x16x32_bf16 v[68:71], v[156:159], v[220:223], v[68:71]
	v_mfma_f32_16x16x32_bf16 v[68:71], v[152:155], v[206:209], v[68:71]
	v_mfma_f32_16x16x32_bf16 v[80:83], v[144:147], v[206:209], v[80:83]
	v_mfma_f32_16x16x32_bf16 v[80:83], v[148:151], v[220:223], v[80:83]
	v_mfma_f32_16x16x32_bf16 v[84:87], v[140:143], v[220:223], v[84:87]
	v_mfma_f32_16x16x32_bf16 v[84:87], v[136:139], v[206:209], v[84:87]
	s_barrier
	s_add_i32 s80, s85, s59
	v_lshl_add_u64 v[224:225], s[82:83], 0, v[172:173]
	s_mov_b32 m0, s80
	s_nop 0
	global_load_lds_dwordx4 v[224:225], off
	v_lshl_add_u64 v[226:227], v[224:225], 0, s[40:41]
	s_add_i32 m0, s80, 0x2000
	s_add_i32 s79, s79, s59
	global_load_lds_dwordx4 v[226:227], off
	v_lshl_add_u64 v[226:227], v[224:225], 0, s[4:5]
	s_mov_b32 m0, s79
	s_nop 0
	global_load_lds_dwordx4 v[226:227], off
	v_lshl_add_u64 v[226:227], v[224:225], 0, s[6:7]
	s_add_i32 m0, s79, 0x2000
	s_nop 0
	global_load_lds_dwordx4 v[226:227], off
	v_lshl_add_u64 v[226:227], s[50:51], 0, v[128:129]
	s_mov_b32 m0, s62
	v_lshl_add_u64 v[228:229], v[226:227], 0, s[40:41]
	global_load_lds_dwordx4 v[226:227], off
	s_mov_b32 m0, s63
	s_nop 0
	global_load_lds_dwordx4 v[228:229], off
	ds_read_b128 v[182:185], v134 offset:16384
	ds_read_b128 v[186:189], v134 offset:17408
	ds_read_b128 v[190:193], v134 offset:18432
	ds_read_b128 v[194:197], v134 offset:19456
	ds_read_b128 v[198:201], v134 offset:20480
	ds_read_b128 v[202:205], v134 offset:21504
	ds_read_b128 v[206:209], v134 offset:22528
	ds_read_b128 v[220:223], v134 offset:23552
	s_waitcnt vmcnt(8)
	s_waitcnt lgkmcnt(0)
	s_barrier
	s_waitcnt lgkmcnt(0)
	v_mfma_f32_16x16x32_bf16 v[60:63], v[136:139], v[182:185], v[60:63]
	v_mfma_f32_16x16x32_bf16 v[60:63], v[140:143], v[186:189], v[60:63]
	v_mfma_f32_16x16x32_bf16 v[56:59], v[148:151], v[186:189], v[56:59]
	v_mfma_f32_16x16x32_bf16 v[56:59], v[144:147], v[182:185], v[56:59]
	v_mfma_f32_16x16x32_bf16 v[44:47], v[152:155], v[182:185], v[44:47]
	v_mfma_f32_16x16x32_bf16 v[44:47], v[156:159], v[186:189], v[44:47]
	v_mfma_f32_16x16x32_bf16 v[40:43], v[164:167], v[186:189], v[40:43]
	v_mfma_f32_16x16x32_bf16 v[40:43], v[160:163], v[182:185], v[40:43]
	v_mfma_f32_16x16x32_bf16 v[24:27], v[160:163], v[190:193], v[24:27]
	v_mfma_f32_16x16x32_bf16 v[24:27], v[164:167], v[194:197], v[24:27]
	v_mfma_f32_16x16x32_bf16 v[28:31], v[156:159], v[194:197], v[28:31]
	v_mfma_f32_16x16x32_bf16 v[28:31], v[152:155], v[190:193], v[28:31]
	v_mfma_f32_16x16x32_bf16 v[48:51], v[144:147], v[190:193], v[48:51]
	v_mfma_f32_16x16x32_bf16 v[48:51], v[148:151], v[194:197], v[48:51]
	v_mfma_f32_16x16x32_bf16 v[52:55], v[140:143], v[194:197], v[52:55]
	v_mfma_f32_16x16x32_bf16 v[52:55], v[136:139], v[190:193], v[52:55]
	v_mfma_f32_16x16x32_bf16 v[36:39], v[136:139], v[198:201], v[36:39]
	v_mfma_f32_16x16x32_bf16 v[36:39], v[140:143], v[202:205], v[36:39]
	v_mfma_f32_16x16x32_bf16 v[32:35], v[148:151], v[202:205], v[32:35]
	v_mfma_f32_16x16x32_bf16 v[32:35], v[144:147], v[198:201], v[32:35]
	v_mfma_f32_16x16x32_bf16 v[12:15], v[152:155], v[198:201], v[12:15]
	v_mfma_f32_16x16x32_bf16 v[12:15], v[156:159], v[202:205], v[12:15]
	v_mfma_f32_16x16x32_bf16 v[8:11], v[164:167], v[202:205], v[8:11]
	v_mfma_f32_16x16x32_bf16 v[8:11], v[160:163], v[198:201], v[8:11]
	v_mfma_f32_16x16x32_bf16 v[0:3], v[160:163], v[206:209], v[0:3]
	v_mfma_f32_16x16x32_bf16 v[0:3], v[164:167], v[220:223], v[0:3]
	v_mfma_f32_16x16x32_bf16 v[4:7], v[156:159], v[220:223], v[4:7]
	v_mfma_f32_16x16x32_bf16 v[4:7], v[152:155], v[206:209], v[4:7]
	v_mfma_f32_16x16x32_bf16 v[16:19], v[144:147], v[206:209], v[16:19]
	v_mfma_f32_16x16x32_bf16 v[16:19], v[148:151], v[220:223], v[16:19]
	v_mfma_f32_16x16x32_bf16 v[20:23], v[140:143], v[220:223], v[20:23]
	v_mfma_f32_16x16x32_bf16 v[20:23], v[136:139], v[206:209], v[20:23]
	s_barrier
	s_mov_b32 m0, s68
	v_lshl_add_u64 v[228:229], v[226:227], 0, s[4:5]
	global_load_lds_dwordx4 v[228:229], off
	v_lshl_add_u64 v[228:229], v[226:227], 0, s[6:7]
	s_mov_b32 m0, s69
	s_nop 0
	global_load_lds_dwordx4 v[228:229], off
	s_add_i32 s50, 0, 0x18000
	v_add_u32_e32 v135, s50, v133
	s_add_i32 s51, 0, 0x1c000
	ds_read_b128 v[136:139], v135
	ds_read_b128 v[140:143], v135 offset:1024
	ds_read_b128 v[144:147], v135 offset:2048
	ds_read_b128 v[148:151], v135 offset:3072
	v_add_u32_e32 v135, s51, v133
	ds_read_b128 v[152:155], v135
	ds_read_b128 v[156:159], v135 offset:1024
	ds_read_b128 v[160:163], v135 offset:2048
	ds_read_b128 v[164:167], v135 offset:3072
	ds_read_b128 v[182:185], v134 offset:32768
	ds_read_b128 v[186:189], v134 offset:33792
	ds_read_b128 v[190:193], v134 offset:34816
	ds_read_b128 v[194:197], v134 offset:35840
	ds_read_b128 v[198:201], v134 offset:36864
	ds_read_b128 v[202:205], v134 offset:37888
	ds_read_b128 v[206:209], v134 offset:38912
	ds_read_b128 v[220:223], v134 offset:39936
	s_nop 0
	s_waitcnt vmcnt(8)
	s_waitcnt lgkmcnt(0)
	s_barrier
	s_waitcnt lgkmcnt(0)
	v_mfma_f32_16x16x32_bf16 v[124:127], v[136:139], v[182:185], v[124:127]
	v_mfma_f32_16x16x32_bf16 v[124:127], v[140:143], v[186:189], v[124:127]
	v_mfma_f32_16x16x32_bf16 v[120:123], v[148:151], v[186:189], v[120:123]
	v_mfma_f32_16x16x32_bf16 v[120:123], v[144:147], v[182:185], v[120:123]
	v_mfma_f32_16x16x32_bf16 v[108:111], v[152:155], v[182:185], v[108:111]
	v_mfma_f32_16x16x32_bf16 v[108:111], v[156:159], v[186:189], v[108:111]
	v_mfma_f32_16x16x32_bf16 v[104:107], v[164:167], v[186:189], v[104:107]
	v_mfma_f32_16x16x32_bf16 v[104:107], v[160:163], v[182:185], v[104:107]
	v_mfma_f32_16x16x32_bf16 v[88:91], v[160:163], v[190:193], v[88:91]
	v_mfma_f32_16x16x32_bf16 v[88:91], v[164:167], v[194:197], v[88:91]
	v_mfma_f32_16x16x32_bf16 v[92:95], v[156:159], v[194:197], v[92:95]
	v_mfma_f32_16x16x32_bf16 v[92:95], v[152:155], v[190:193], v[92:95]
	v_mfma_f32_16x16x32_bf16 v[112:115], v[144:147], v[190:193], v[112:115]
	v_mfma_f32_16x16x32_bf16 v[112:115], v[148:151], v[194:197], v[112:115]
	v_mfma_f32_16x16x32_bf16 v[116:119], v[140:143], v[194:197], v[116:119]
	v_mfma_f32_16x16x32_bf16 v[116:119], v[136:139], v[190:193], v[116:119]
	v_mfma_f32_16x16x32_bf16 v[100:103], v[136:139], v[198:201], v[100:103]
	v_mfma_f32_16x16x32_bf16 v[100:103], v[140:143], v[202:205], v[100:103]
	v_mfma_f32_16x16x32_bf16 v[96:99], v[148:151], v[202:205], v[96:99]
	v_mfma_f32_16x16x32_bf16 v[96:99], v[144:147], v[198:201], v[96:99]
	v_mfma_f32_16x16x32_bf16 v[76:79], v[152:155], v[198:201], v[76:79]
	v_mfma_f32_16x16x32_bf16 v[76:79], v[156:159], v[202:205], v[76:79]
	v_mfma_f32_16x16x32_bf16 v[72:75], v[164:167], v[202:205], v[72:75]
	v_mfma_f32_16x16x32_bf16 v[72:75], v[160:163], v[198:201], v[72:75]
	v_mfma_f32_16x16x32_bf16 v[64:67], v[160:163], v[206:209], v[64:67]
	v_mfma_f32_16x16x32_bf16 v[64:67], v[164:167], v[220:223], v[64:67]
	v_mfma_f32_16x16x32_bf16 v[68:71], v[156:159], v[220:223], v[68:71]
	v_mfma_f32_16x16x32_bf16 v[68:71], v[152:155], v[206:209], v[68:71]
	v_mfma_f32_16x16x32_bf16 v[80:83], v[144:147], v[206:209], v[80:83]
	v_mfma_f32_16x16x32_bf16 v[80:83], v[148:151], v[220:223], v[80:83]
	v_mfma_f32_16x16x32_bf16 v[84:87], v[140:143], v[220:223], v[84:87]
	v_mfma_f32_16x16x32_bf16 v[84:87], v[136:139], v[206:209], v[84:87]
	s_barrier
	s_add_i32 s50, s50, s59
	v_lshl_add_u64 v[228:229], v[224:225], 0, s[10:11]
	s_mov_b32 m0, s50
	s_nop 0
	global_load_lds_dwordx4 v[228:229], off
	v_lshl_add_u64 v[228:229], v[224:225], 0, s[12:13]
	s_add_i32 m0, s50, 0x2000
	s_add_i32 s50, s51, s59
	global_load_lds_dwordx4 v[228:229], off
	v_lshl_add_u64 v[228:229], v[224:225], 0, s[14:15]
	s_mov_b32 m0, s50
	v_lshl_add_u64 v[224:225], v[224:225], 0, s[16:17]
	global_load_lds_dwordx4 v[228:229], off
	s_add_i32 m0, s50, 0x2000
	s_nop 0
	global_load_lds_dwordx4 v[224:225], off
	v_lshl_add_u64 v[224:225], v[226:227], 0, s[10:11]
	s_mov_b32 m0, s72
	s_nop 0
	global_load_lds_dwordx4 v[224:225], off
	v_lshl_add_u64 v[224:225], v[226:227], 0, s[12:13]
	s_mov_b32 m0, s73
	s_nop 0
	global_load_lds_dwordx4 v[224:225], off
	ds_read_b128 v[182:185], v134 offset:49152
	ds_read_b128 v[186:189], v134 offset:50176
	ds_read_b128 v[190:193], v134 offset:51200
	ds_read_b128 v[194:197], v134 offset:52224
	ds_read_b128 v[198:201], v134 offset:53248
	ds_read_b128 v[202:205], v134 offset:54272
	ds_read_b128 v[206:209], v134 offset:55296
	ds_read_b128 v[220:223], v134 offset:56320
	s_waitcnt vmcnt(8)
	s_waitcnt lgkmcnt(0)
	s_barrier
	s_waitcnt lgkmcnt(0)
	v_mfma_f32_16x16x32_bf16 v[60:63], v[136:139], v[182:185], v[60:63]
	v_mfma_f32_16x16x32_bf16 v[60:63], v[140:143], v[186:189], v[60:63]
	v_mfma_f32_16x16x32_bf16 v[56:59], v[148:151], v[186:189], v[56:59]
	v_mfma_f32_16x16x32_bf16 v[56:59], v[144:147], v[182:185], v[56:59]
	v_mfma_f32_16x16x32_bf16 v[44:47], v[152:155], v[182:185], v[44:47]
	v_mfma_f32_16x16x32_bf16 v[44:47], v[156:159], v[186:189], v[44:47]
	v_mfma_f32_16x16x32_bf16 v[40:43], v[164:167], v[186:189], v[40:43]
	v_mfma_f32_16x16x32_bf16 v[40:43], v[160:163], v[182:185], v[40:43]
	v_mfma_f32_16x16x32_bf16 v[24:27], v[160:163], v[190:193], v[24:27]
	v_mfma_f32_16x16x32_bf16 v[24:27], v[164:167], v[194:197], v[24:27]
	v_mfma_f32_16x16x32_bf16 v[28:31], v[156:159], v[194:197], v[28:31]
	v_mfma_f32_16x16x32_bf16 v[28:31], v[152:155], v[190:193], v[28:31]
	v_mfma_f32_16x16x32_bf16 v[48:51], v[144:147], v[190:193], v[48:51]
	v_mfma_f32_16x16x32_bf16 v[48:51], v[148:151], v[194:197], v[48:51]
	v_mfma_f32_16x16x32_bf16 v[52:55], v[140:143], v[194:197], v[52:55]
	v_mfma_f32_16x16x32_bf16 v[52:55], v[136:139], v[190:193], v[52:55]
	v_mfma_f32_16x16x32_bf16 v[36:39], v[136:139], v[198:201], v[36:39]
	v_mfma_f32_16x16x32_bf16 v[36:39], v[140:143], v[202:205], v[36:39]
	v_mfma_f32_16x16x32_bf16 v[32:35], v[148:151], v[202:205], v[32:35]
	v_mfma_f32_16x16x32_bf16 v[32:35], v[144:147], v[198:201], v[32:35]
	v_mfma_f32_16x16x32_bf16 v[12:15], v[152:155], v[198:201], v[12:15]
	v_mfma_f32_16x16x32_bf16 v[12:15], v[156:159], v[202:205], v[12:15]
	v_mfma_f32_16x16x32_bf16 v[8:11], v[164:167], v[202:205], v[8:11]
	v_mfma_f32_16x16x32_bf16 v[8:11], v[160:163], v[198:201], v[8:11]
	v_mfma_f32_16x16x32_bf16 v[0:3], v[160:163], v[206:209], v[0:3]
	v_mfma_f32_16x16x32_bf16 v[0:3], v[164:167], v[220:223], v[0:3]
	v_mfma_f32_16x16x32_bf16 v[4:7], v[156:159], v[220:223], v[4:7]
	v_mfma_f32_16x16x32_bf16 v[4:7], v[152:155], v[206:209], v[4:7]
	v_mfma_f32_16x16x32_bf16 v[16:19], v[144:147], v[206:209], v[16:19]
	v_mfma_f32_16x16x32_bf16 v[16:19], v[148:151], v[220:223], v[16:19]
	v_mfma_f32_16x16x32_bf16 v[20:23], v[140:143], v[220:223], v[20:23]
	v_mfma_f32_16x16x32_bf16 v[20:23], v[136:139], v[206:209], v[20:23]
	s_barrier
	s_cmp_gt_u32 s78, 13
	s_cbranch_scc0 .LBB0_856
	s_and_b64 vcc, exec, s[8:9]
	s_cbranch_vccz .LBB0_859
	s_barrier

.LBB0_970:
	s_add_i32 s21, s21, 2
	s_mov_b32 s38, s21
	s_ashr_i32 s39, s38, 31
	s_lshl_b64 s[74:75], s[38:39], 7
	s_add_u32 s39, s74, 0x100
	s_addc_u32 s73, s75, 0
	s_add_u32 s76, s34, s39
	s_addc_u32 s77, s35, s73
	s_add_u32 s78, s30, s39
	s_addc_u32 s73, s31, s73
	s_cmp_eq_u32 s38, 14
	s_cselect_b32 s39, s67, s77
	s_cselect_b32 s38, s68, s76
	s_cselect_b32 s77, s23, s73
	s_cselect_b32 s76, s66, s78
	s_add_u32 s74, s34, s74
	s_addc_u32 s75, s35, s75
	v_lshl_add_u64 v[208:209], s[74:75], 0, v[130:131]
	s_mov_b32 m0, s59
	v_lshl_add_u64 v[216:217], v[208:209], 0, s[14:15]
	global_load_lds_dwordx4 v[216:217], off
	v_lshl_add_u64 v[208:209], v[208:209], 0, s[16:17]
	s_mov_b32 m0, s60
	s_nop 0
	global_load_lds_dwordx4 v[208:209], off
	ds_read_b128 v[144:147], v140
	ds_read_b128 v[148:151], v140 offset:1024
	ds_read_b128 v[152:155], v140 offset:2048
	ds_read_b128 v[156:159], v140 offset:3072
	ds_read_b128 v[160:163], v141
	ds_read_b128 v[164:167], v141 offset:1024
	ds_read_b128 v[172:175], v141 offset:2048
	ds_read_b128 v[176:179], v141 offset:3072
	ds_read_b128 v[180:183], v142
	ds_read_b128 v[184:187], v142 offset:1024
	ds_read_b128 v[188:191], v142 offset:2048
	ds_read_b128 v[192:195], v142 offset:3072
	ds_read_b128 v[196:199], v142 offset:4096
	ds_read_b128 v[200:203], v142 offset:5120
	ds_read_b128 v[204:207], v142 offset:6144
	ds_read_b128 v[212:215], v142 offset:7168
	s_waitcnt vmcnt(8)
	s_waitcnt lgkmcnt(0)
	s_barrier
	s_waitcnt lgkmcnt(0)
	v_mfma_f32_16x16x32_bf16 v[124:127], v[144:147], v[180:183], v[124:127]
	v_mfma_f32_16x16x32_bf16 v[124:127], v[148:151], v[184:187], v[124:127]
	v_mfma_f32_16x16x32_bf16 v[112:115], v[156:159], v[184:187], v[112:115]
	v_mfma_f32_16x16x32_bf16 v[112:115], v[152:155], v[180:183], v[112:115]
	v_mfma_f32_16x16x32_bf16 v[120:123], v[160:163], v[180:183], v[120:123]
	v_mfma_f32_16x16x32_bf16 v[120:123], v[164:167], v[184:187], v[120:123]
	v_mfma_f32_16x16x32_bf16 v[116:119], v[176:179], v[184:187], v[116:119]
	v_mfma_f32_16x16x32_bf16 v[116:119], v[172:175], v[180:183], v[116:119]
	v_mfma_f32_16x16x32_bf16 v[100:103], v[172:175], v[188:191], v[100:103]
	v_mfma_f32_16x16x32_bf16 v[100:103], v[176:179], v[192:195], v[100:103]
	v_mfma_f32_16x16x32_bf16 v[104:107], v[164:167], v[192:195], v[104:107]
	v_mfma_f32_16x16x32_bf16 v[104:107], v[160:163], v[188:191], v[104:107]
	v_mfma_f32_16x16x32_bf16 v[96:99], v[152:155], v[188:191], v[96:99]
	v_mfma_f32_16x16x32_bf16 v[96:99], v[156:159], v[192:195], v[96:99]
	v_mfma_f32_16x16x32_bf16 v[108:111], v[148:151], v[192:195], v[108:111]
	v_mfma_f32_16x16x32_bf16 v[108:111], v[144:147], v[188:191], v[108:111]
	v_mfma_f32_16x16x32_bf16 v[92:95], v[144:147], v[196:199], v[92:95]
	v_mfma_f32_16x16x32_bf16 v[92:95], v[148:151], v[200:203], v[92:95]
	v_mfma_f32_16x16x32_bf16 v[80:83], v[156:159], v[200:203], v[80:83]
	v_mfma_f32_16x16x32_bf16 v[80:83], v[152:155], v[196:199], v[80:83]
	v_mfma_f32_16x16x32_bf16 v[88:91], v[160:163], v[196:199], v[88:91]
	v_mfma_f32_16x16x32_bf16 v[88:91], v[164:167], v[200:203], v[88:91]
	v_mfma_f32_16x16x32_bf16 v[84:87], v[176:179], v[200:203], v[84:87]
	v_mfma_f32_16x16x32_bf16 v[84:87], v[172:175], v[196:199], v[84:87]
	v_mfma_f32_16x16x32_bf16 v[68:71], v[172:175], v[204:207], v[68:71]
	v_mfma_f32_16x16x32_bf16 v[68:71], v[176:179], v[212:215], v[68:71]
	v_mfma_f32_16x16x32_bf16 v[72:75], v[164:167], v[212:215], v[72:75]
	v_mfma_f32_16x16x32_bf16 v[72:75], v[160:163], v[204:207], v[72:75]
	v_mfma_f32_16x16x32_bf16 v[64:67], v[152:155], v[204:207], v[64:67]
	v_mfma_f32_16x16x32_bf16 v[64:67], v[156:159], v[212:215], v[64:67]
	v_mfma_f32_16x16x32_bf16 v[76:79], v[148:151], v[212:215], v[76:79]
	v_mfma_f32_16x16x32_bf16 v[76:79], v[144:147], v[204:207], v[76:79]
	s_barrier
	s_mov_b32 m0, s61
	v_lshl_add_u64 v[208:209], s[76:77], 0, v[128:129]
	global_load_lds_dwordx4 v[208:209], off
	v_lshl_add_u64 v[216:217], v[208:209], 0, s[0:1]
	s_mov_b32 m0, s62
	s_nop 0
	global_load_lds_dwordx4 v[216:217], off
	v_lshl_add_u64 v[216:217], v[208:209], 0, s[2:3]
	s_mov_b32 m0, s63
	s_nop 0
	global_load_lds_dwordx4 v[216:217], off
	v_lshl_add_u64 v[216:217], v[208:209], 0, s[4:5]
	s_mov_b32 m0, s64
	s_nop 0
	global_load_lds_dwordx4 v[216:217], off
	v_lshl_add_u64 v[216:217], s[38:39], 0, v[130:131]
	s_mov_b32 m0, s48
	v_lshl_add_u64 v[218:219], v[216:217], 0, s[0:1]
	global_load_lds_dwordx4 v[216:217], off
	s_mov_b32 m0, s49
	s_nop 0
	global_load_lds_dwordx4 v[218:219], off
	ds_read_b128 v[180:183], v142 offset:16384
	ds_read_b128 v[184:187], v142 offset:17408
	ds_read_b128 v[188:191], v142 offset:18432
	ds_read_b128 v[192:195], v142 offset:19456
	ds_read_b128 v[196:199], v142 offset:20480
	ds_read_b128 v[200:203], v142 offset:21504
	ds_read_b128 v[204:207], v142 offset:22528
	ds_read_b128 v[212:215], v142 offset:23552
	s_waitcnt vmcnt(8)
	s_waitcnt lgkmcnt(0)
	s_barrier
	s_waitcnt lgkmcnt(0)
	v_mfma_f32_16x16x32_bf16 v[60:63], v[144:147], v[180:183], v[60:63]
	v_mfma_f32_16x16x32_bf16 v[60:63], v[148:151], v[184:187], v[60:63]
	v_mfma_f32_16x16x32_bf16 v[48:51], v[156:159], v[184:187], v[48:51]
	v_mfma_f32_16x16x32_bf16 v[48:51], v[152:155], v[180:183], v[48:51]
	v_mfma_f32_16x16x32_bf16 v[56:59], v[160:163], v[180:183], v[56:59]
	v_mfma_f32_16x16x32_bf16 v[56:59], v[164:167], v[184:187], v[56:59]
	v_mfma_f32_16x16x32_bf16 v[52:55], v[176:179], v[184:187], v[52:55]
	v_mfma_f32_16x16x32_bf16 v[52:55], v[172:175], v[180:183], v[52:55]
	v_mfma_f32_16x16x32_bf16 v[36:39], v[172:175], v[188:191], v[36:39]
	v_mfma_f32_16x16x32_bf16 v[36:39], v[176:179], v[192:195], v[36:39]
	v_mfma_f32_16x16x32_bf16 v[40:43], v[164:167], v[192:195], v[40:43]
	v_mfma_f32_16x16x32_bf16 v[40:43], v[160:163], v[188:191], v[40:43]
	v_mfma_f32_16x16x32_bf16 v[32:35], v[152:155], v[188:191], v[32:35]
	v_mfma_f32_16x16x32_bf16 v[32:35], v[156:159], v[192:195], v[32:35]
	v_mfma_f32_16x16x32_bf16 v[44:47], v[148:151], v[192:195], v[44:47]
	v_mfma_f32_16x16x32_bf16 v[44:47], v[144:147], v[188:191], v[44:47]
	v_mfma_f32_16x16x32_bf16 v[28:31], v[144:147], v[196:199], v[28:31]
	v_mfma_f32_16x16x32_bf16 v[28:31], v[148:151], v[200:203], v[28:31]
	v_mfma_f32_16x16x32_bf16 v[16:19], v[156:159], v[200:203], v[16:19]
	v_mfma_f32_16x16x32_bf16 v[16:19], v[152:155], v[196:199], v[16:19]
	v_mfma_f32_16x16x32_bf16 v[24:27], v[160:163], v[196:199], v[24:27]
	v_mfma_f32_16x16x32_bf16 v[24:27], v[164:167], v[200:203], v[24:27]
	v_mfma_f32_16x16x32_bf16 v[20:23], v[176:179], v[200:203], v[20:23]
	v_mfma_f32_16x16x32_bf16 v[20:23], v[172:175], v[196:199], v[20:23]
	v_mfma_f32_16x16x32_bf16 v[4:7], v[172:175], v[204:207], v[4:7]
	v_mfma_f32_16x16x32_bf16 v[4:7], v[176:179], v[212:215], v[4:7]
	v_mfma_f32_16x16x32_bf16 v[8:11], v[164:167], v[212:215], v[8:11]
	v_mfma_f32_16x16x32_bf16 v[8:11], v[160:163], v[204:207], v[8:11]
	v_mfma_f32_16x16x32_bf16 v[0:3], v[152:155], v[204:207], v[0:3]
	v_mfma_f32_16x16x32_bf16 v[0:3], v[156:159], v[212:215], v[0:3]
	v_mfma_f32_16x16x32_bf16 v[12:15], v[148:151], v[212:215], v[12:15]
	v_mfma_f32_16x16x32_bf16 v[12:15], v[144:147], v[204:207], v[12:15]
	s_barrier
	s_mov_b32 m0, s50
	v_lshl_add_u64 v[218:219], v[216:217], 0, s[2:3]
	global_load_lds_dwordx4 v[218:219], off
	v_lshl_add_u64 v[218:219], v[216:217], 0, s[4:5]
	s_mov_b32 m0, s51
	s_nop 0
	global_load_lds_dwordx4 v[218:219], off
	ds_read_b128 v[144:147], v143
	ds_read_b128 v[148:151], v143 offset:1024
	ds_read_b128 v[152:155], v143 offset:2048
	ds_read_b128 v[156:159], v143 offset:3072
	ds_read_b128 v[160:163], v136
	ds_read_b128 v[164:167], v136 offset:1024
	ds_read_b128 v[172:175], v136 offset:2048
	ds_read_b128 v[176:179], v136 offset:3072
	ds_read_b128 v[180:183], v142 offset:32768
	ds_read_b128 v[184:187], v142 offset:33792
	ds_read_b128 v[188:191], v142 offset:34816
	ds_read_b128 v[192:195], v142 offset:35840
	ds_read_b128 v[196:199], v142 offset:36864
	ds_read_b128 v[200:203], v142 offset:37888
	ds_read_b128 v[204:207], v142 offset:38912
	ds_read_b128 v[212:215], v142 offset:39936
	s_waitcnt vmcnt(8)
	s_waitcnt lgkmcnt(0)
	s_barrier
	s_waitcnt lgkmcnt(0)
	v_mfma_f32_16x16x32_bf16 v[124:127], v[144:147], v[180:183], v[124:127]
	v_mfma_f32_16x16x32_bf16 v[124:127], v[148:151], v[184:187], v[124:127]
	v_mfma_f32_16x16x32_bf16 v[112:115], v[156:159], v[184:187], v[112:115]
	v_mfma_f32_16x16x32_bf16 v[112:115], v[152:155], v[180:183], v[112:115]
	v_mfma_f32_16x16x32_bf16 v[120:123], v[160:163], v[180:183], v[120:123]
	v_mfma_f32_16x16x32_bf16 v[120:123], v[164:167], v[184:187], v[120:123]
	v_mfma_f32_16x16x32_bf16 v[116:119], v[176:179], v[184:187], v[116:119]
	v_mfma_f32_16x16x32_bf16 v[116:119], v[172:175], v[180:183], v[116:119]
	v_mfma_f32_16x16x32_bf16 v[100:103], v[172:175], v[188:191], v[100:103]
	v_mfma_f32_16x16x32_bf16 v[100:103], v[176:179], v[192:195], v[100:103]
	v_mfma_f32_16x16x32_bf16 v[104:107], v[164:167], v[192:195], v[104:107]
	v_mfma_f32_16x16x32_bf16 v[104:107], v[160:163], v[188:191], v[104:107]
	v_mfma_f32_16x16x32_bf16 v[96:99], v[152:155], v[188:191], v[96:99]
	v_mfma_f32_16x16x32_bf16 v[96:99], v[156:159], v[192:195], v[96:99]
	v_mfma_f32_16x16x32_bf16 v[108:111], v[148:151], v[192:195], v[108:111]
	v_mfma_f32_16x16x32_bf16 v[108:111], v[144:147], v[188:191], v[108:111]
	v_mfma_f32_16x16x32_bf16 v[92:95], v[144:147], v[196:199], v[92:95]
	v_mfma_f32_16x16x32_bf16 v[92:95], v[148:151], v[200:203], v[92:95]
	v_mfma_f32_16x16x32_bf16 v[80:83], v[156:159], v[200:203], v[80:83]
	v_mfma_f32_16x16x32_bf16 v[80:83], v[152:155], v[196:199], v[80:83]
	v_mfma_f32_16x16x32_bf16 v[88:91], v[160:163], v[196:199], v[88:91]
	v_mfma_f32_16x16x32_bf16 v[88:91], v[164:167], v[200:203], v[88:91]
	v_mfma_f32_16x16x32_bf16 v[84:87], v[176:179], v[200:203], v[84:87]
	v_mfma_f32_16x16x32_bf16 v[84:87], v[172:175], v[196:199], v[84:87]
	v_mfma_f32_16x16x32_bf16 v[68:71], v[172:175], v[204:207], v[68:71]
	v_mfma_f32_16x16x32_bf16 v[68:71], v[176:179], v[212:215], v[68:71]
	v_mfma_f32_16x16x32_bf16 v[72:75], v[164:167], v[212:215], v[72:75]
	v_mfma_f32_16x16x32_bf16 v[72:75], v[160:163], v[204:207], v[72:75]
	v_mfma_f32_16x16x32_bf16 v[64:67], v[152:155], v[204:207], v[64:67]
	v_mfma_f32_16x16x32_bf16 v[64:67], v[156:159], v[212:215], v[64:67]
	v_mfma_f32_16x16x32_bf16 v[76:79], v[148:151], v[212:215], v[76:79]
	v_mfma_f32_16x16x32_bf16 v[76:79], v[144:147], v[204:207], v[76:79]
	s_barrier
	s_mov_b32 m0, s69
	v_lshl_add_u64 v[218:219], v[208:209], 0, s[10:11]
	global_load_lds_dwordx4 v[218:219], off
	v_lshl_add_u64 v[218:219], v[208:209], 0, s[12:13]
	s_mov_b32 m0, s70
	s_nop 0
	global_load_lds_dwordx4 v[218:219], off
	v_lshl_add_u64 v[218:219], v[208:209], 0, s[14:15]
	s_mov_b32 m0, s71
	v_lshl_add_u64 v[208:209], v[208:209], 0, s[16:17]
	global_load_lds_dwordx4 v[218:219], off
	s_mov_b32 m0, s72
	s_nop 0
	global_load_lds_dwordx4 v[208:209], off
	v_lshl_add_u64 v[208:209], v[216:217], 0, s[10:11]
	s_mov_b32 m0, s53
	s_nop 0
	global_load_lds_dwordx4 v[208:209], off
	v_lshl_add_u64 v[208:209], v[216:217], 0, s[12:13]
	s_mov_b32 m0, s54
	s_nop 0
	global_load_lds_dwordx4 v[208:209], off
	ds_read_b128 v[180:183], v142 offset:49152
	ds_read_b128 v[184:187], v142 offset:50176
	ds_read_b128 v[188:191], v142 offset:51200
	ds_read_b128 v[192:195], v142 offset:52224
	ds_read_b128 v[196:199], v142 offset:53248
	ds_read_b128 v[200:203], v142 offset:54272
	ds_read_b128 v[204:207], v142 offset:55296
	ds_read_b128 v[212:215], v142 offset:56320
	s_waitcnt vmcnt(8)
	s_waitcnt lgkmcnt(0)
	s_barrier
	s_waitcnt lgkmcnt(0)
	v_mfma_f32_16x16x32_bf16 v[60:63], v[144:147], v[180:183], v[60:63]
	v_mfma_f32_16x16x32_bf16 v[60:63], v[148:151], v[184:187], v[60:63]
	v_mfma_f32_16x16x32_bf16 v[48:51], v[156:159], v[184:187], v[48:51]
	v_mfma_f32_16x16x32_bf16 v[48:51], v[152:155], v[180:183], v[48:51]
	v_mfma_f32_16x16x32_bf16 v[56:59], v[160:163], v[180:183], v[56:59]
	v_mfma_f32_16x16x32_bf16 v[56:59], v[164:167], v[184:187], v[56:59]
	v_mfma_f32_16x16x32_bf16 v[52:55], v[176:179], v[184:187], v[52:55]
	v_mfma_f32_16x16x32_bf16 v[52:55], v[172:175], v[180:183], v[52:55]
	v_mfma_f32_16x16x32_bf16 v[36:39], v[172:175], v[188:191], v[36:39]
	v_mfma_f32_16x16x32_bf16 v[36:39], v[176:179], v[192:195], v[36:39]
	v_mfma_f32_16x16x32_bf16 v[40:43], v[164:167], v[192:195], v[40:43]
	v_mfma_f32_16x16x32_bf16 v[40:43], v[160:163], v[188:191], v[40:43]
	v_mfma_f32_16x16x32_bf16 v[32:35], v[152:155], v[188:191], v[32:35]
	v_mfma_f32_16x16x32_bf16 v[32:35], v[156:159], v[192:195], v[32:35]
	v_mfma_f32_16x16x32_bf16 v[44:47], v[148:151], v[192:195], v[44:47]
	v_mfma_f32_16x16x32_bf16 v[44:47], v[144:147], v[188:191], v[44:47]
	v_mfma_f32_16x16x32_bf16 v[28:31], v[144:147], v[196:199], v[28:31]
	v_mfma_f32_16x16x32_bf16 v[28:31], v[148:151], v[200:203], v[28:31]
	v_mfma_f32_16x16x32_bf16 v[16:19], v[156:159], v[200:203], v[16:19]
	v_mfma_f32_16x16x32_bf16 v[16:19], v[152:155], v[196:199], v[16:19]
	v_mfma_f32_16x16x32_bf16 v[24:27], v[160:163], v[196:199], v[24:27]
	v_mfma_f32_16x16x32_bf16 v[24:27], v[164:167], v[200:203], v[24:27]
	v_mfma_f32_16x16x32_bf16 v[20:23], v[176:179], v[200:203], v[20:23]
	v_mfma_f32_16x16x32_bf16 v[20:23], v[172:175], v[196:199], v[20:23]
	v_mfma_f32_16x16x32_bf16 v[4:7], v[172:175], v[204:207], v[4:7]
	v_mfma_f32_16x16x32_bf16 v[4:7], v[176:179], v[212:215], v[4:7]
	v_mfma_f32_16x16x32_bf16 v[8:11], v[164:167], v[212:215], v[8:11]
	v_mfma_f32_16x16x32_bf16 v[8:11], v[160:163], v[204:207], v[8:11]
	v_mfma_f32_16x16x32_bf16 v[0:3], v[152:155], v[204:207], v[0:3]
	v_mfma_f32_16x16x32_bf16 v[0:3], v[156:159], v[212:215], v[0:3]
	v_mfma_f32_16x16x32_bf16 v[12:15], v[148:151], v[212:215], v[12:15]
	v_mfma_f32_16x16x32_bf16 v[12:15], v[144:147], v[204:207], v[12:15]
	s_barrier
	s_cmp_gt_u32 s21, 13
	s_cbranch_scc0 .LBB0_970
	s_and_b64 vcc, exec, s[18:19]
	s_cbranch_vccz .LBB0_973
	s_barrier

.LBB0_1046:
	s_add_i32 s55, s55, 2
	s_mov_b32 s56, s55
	s_ashr_i32 s57, s56, 31
	s_lshl_b64 s[58:59], s[56:57], 7
	s_add_u32 s57, s58, 0x100
	s_addc_u32 s60, s59, 0
	s_add_u32 s61, s24, s57
	s_addc_u32 s62, s25, s60
	s_add_u32 s63, s22, s57
	s_addc_u32 s60, s23, s60
	s_cmp_eq_u32 s56, 42
	s_cselect_b32 s57, s1, s62
	s_cselect_b32 s56, s0, s61
	s_cselect_b32 s61, s27, s60
	s_cselect_b32 s60, s26, s63
	v_lshl_add_u64 v[208:209], v[136:137], 0, s[58:59]
	v_lshl_add_u64 v[216:217], v[208:209], 0, s[12:13]
	s_add_i32 m0, s39, 0xc000
	s_nop 0
	global_load_lds_dwordx4 v[216:217], off
	v_lshl_add_u64 v[208:209], v[208:209], 0, s[14:15]
	s_add_i32 m0, s39, 0xe000
	s_nop 0
	global_load_lds_dwordx4 v[208:209], off
	ds_read_b128 v[144:147], v140
	ds_read_b128 v[148:151], v140 offset:1024
	ds_read_b128 v[152:155], v140 offset:2048
	ds_read_b128 v[156:159], v140 offset:3072
	ds_read_b128 v[160:163], v141
	ds_read_b128 v[164:167], v141 offset:1024
	ds_read_b128 v[172:175], v141 offset:2048
	ds_read_b128 v[176:179], v141 offset:3072
	ds_read_b128 v[180:183], v142
	ds_read_b128 v[184:187], v142 offset:1024
	ds_read_b128 v[188:191], v142 offset:2048
	ds_read_b128 v[192:195], v142 offset:3072
	ds_read_b128 v[196:199], v142 offset:4096
	ds_read_b128 v[200:203], v142 offset:5120
	ds_read_b128 v[204:207], v142 offset:6144
	ds_read_b128 v[212:215], v142 offset:7168
	s_waitcnt vmcnt(8)
	s_waitcnt lgkmcnt(0)
	s_barrier
	s_waitcnt lgkmcnt(0)
	v_mfma_f32_16x16x32_bf16 v[124:127], v[144:147], v[180:183], v[124:127]
	v_mfma_f32_16x16x32_bf16 v[124:127], v[148:151], v[184:187], v[124:127]
	v_mfma_f32_16x16x32_bf16 v[120:123], v[156:159], v[184:187], v[120:123]
	v_mfma_f32_16x16x32_bf16 v[120:123], v[152:155], v[180:183], v[120:123]
	v_mfma_f32_16x16x32_bf16 v[108:111], v[160:163], v[180:183], v[108:111]
	v_mfma_f32_16x16x32_bf16 v[108:111], v[164:167], v[184:187], v[108:111]
	v_mfma_f32_16x16x32_bf16 v[104:107], v[176:179], v[184:187], v[104:107]
	v_mfma_f32_16x16x32_bf16 v[104:107], v[172:175], v[180:183], v[104:107]
	v_mfma_f32_16x16x32_bf16 v[88:91], v[172:175], v[188:191], v[88:91]
	v_mfma_f32_16x16x32_bf16 v[88:91], v[176:179], v[192:195], v[88:91]
	v_mfma_f32_16x16x32_bf16 v[92:95], v[164:167], v[192:195], v[92:95]
	v_mfma_f32_16x16x32_bf16 v[92:95], v[160:163], v[188:191], v[92:95]
	v_mfma_f32_16x16x32_bf16 v[112:115], v[152:155], v[188:191], v[112:115]
	v_mfma_f32_16x16x32_bf16 v[112:115], v[156:159], v[192:195], v[112:115]
	v_mfma_f32_16x16x32_bf16 v[116:119], v[148:151], v[192:195], v[116:119]
	v_mfma_f32_16x16x32_bf16 v[116:119], v[144:147], v[188:191], v[116:119]
	v_mfma_f32_16x16x32_bf16 v[100:103], v[144:147], v[196:199], v[100:103]
	v_mfma_f32_16x16x32_bf16 v[100:103], v[148:151], v[200:203], v[100:103]
	v_mfma_f32_16x16x32_bf16 v[96:99], v[156:159], v[200:203], v[96:99]
	v_mfma_f32_16x16x32_bf16 v[96:99], v[152:155], v[196:199], v[96:99]
	v_mfma_f32_16x16x32_bf16 v[76:79], v[160:163], v[196:199], v[76:79]
	v_mfma_f32_16x16x32_bf16 v[76:79], v[164:167], v[200:203], v[76:79]
	v_mfma_f32_16x16x32_bf16 v[72:75], v[176:179], v[200:203], v[72:75]
	v_mfma_f32_16x16x32_bf16 v[72:75], v[172:175], v[196:199], v[72:75]
	v_mfma_f32_16x16x32_bf16 v[64:67], v[172:175], v[204:207], v[64:67]
	v_mfma_f32_16x16x32_bf16 v[64:67], v[176:179], v[212:215], v[64:67]
	v_mfma_f32_16x16x32_bf16 v[68:71], v[164:167], v[212:215], v[68:71]
	v_mfma_f32_16x16x32_bf16 v[68:71], v[160:163], v[204:207], v[68:71]
	v_mfma_f32_16x16x32_bf16 v[80:83], v[152:155], v[204:207], v[80:83]
	v_mfma_f32_16x16x32_bf16 v[80:83], v[156:159], v[212:215], v[80:83]
	v_mfma_f32_16x16x32_bf16 v[84:87], v[148:151], v[212:215], v[84:87]
	v_mfma_f32_16x16x32_bf16 v[84:87], v[144:147], v[204:207], v[84:87]
	s_barrier
	s_add_i32 s58, s49, s38
	v_lshl_add_u64 v[208:209], s[60:61], 0, v[130:131]
	s_mov_b32 m0, s58
	s_nop 0
	global_load_lds_dwordx4 v[208:209], off
	v_lshl_add_u64 v[216:217], v[208:209], 0, s[2:3]
	s_add_i32 m0, s58, 0x2000
	s_add_i32 s58, s50, s38
	global_load_lds_dwordx4 v[216:217], off
	v_lshl_add_u64 v[216:217], v[208:209], 0, s[4:5]
	s_mov_b32 m0, s58
	s_nop 0
	global_load_lds_dwordx4 v[216:217], off
	v_lshl_add_u64 v[216:217], v[208:209], 0, s[6:7]
	s_add_i32 m0, s58, 0x2000
	s_nop 0
	global_load_lds_dwordx4 v[216:217], off
	v_lshl_add_u64 v[216:217], s[56:57], 0, v[128:129]
	s_mov_b32 m0, s39
	v_lshl_add_u64 v[218:219], v[216:217], 0, s[2:3]
	global_load_lds_dwordx4 v[216:217], off
	s_mov_b32 m0, s40
	s_nop 0
	global_load_lds_dwordx4 v[218:219], off
	ds_read_b128 v[180:183], v142 offset:16384
	ds_read_b128 v[184:187], v142 offset:17408
	ds_read_b128 v[188:191], v142 offset:18432
	ds_read_b128 v[192:195], v142 offset:19456
	ds_read_b128 v[196:199], v142 offset:20480
	ds_read_b128 v[200:203], v142 offset:21504
	ds_read_b128 v[204:207], v142 offset:22528
	ds_read_b128 v[212:215], v142 offset:23552
	s_waitcnt vmcnt(8)
	s_waitcnt lgkmcnt(0)
	s_barrier
	s_waitcnt lgkmcnt(0)
	v_mfma_f32_16x16x32_bf16 v[60:63], v[144:147], v[180:183], v[60:63]
	v_mfma_f32_16x16x32_bf16 v[60:63], v[148:151], v[184:187], v[60:63]
	v_mfma_f32_16x16x32_bf16 v[56:59], v[156:159], v[184:187], v[56:59]
	v_mfma_f32_16x16x32_bf16 v[56:59], v[152:155], v[180:183], v[56:59]
	v_mfma_f32_16x16x32_bf16 v[44:47], v[160:163], v[180:183], v[44:47]
	v_mfma_f32_16x16x32_bf16 v[44:47], v[164:167], v[184:187], v[44:47]
	v_mfma_f32_16x16x32_bf16 v[40:43], v[176:179], v[184:187], v[40:43]
	v_mfma_f32_16x16x32_bf16 v[40:43], v[172:175], v[180:183], v[40:43]
	v_mfma_f32_16x16x32_bf16 v[24:27], v[172:175], v[188:191], v[24:27]
	v_mfma_f32_16x16x32_bf16 v[24:27], v[176:179], v[192:195], v[24:27]
	v_mfma_f32_16x16x32_bf16 v[28:31], v[164:167], v[192:195], v[28:31]
	v_mfma_f32_16x16x32_bf16 v[28:31], v[160:163], v[188:191], v[28:31]
	v_mfma_f32_16x16x32_bf16 v[48:51], v[152:155], v[188:191], v[48:51]
	v_mfma_f32_16x16x32_bf16 v[48:51], v[156:159], v[192:195], v[48:51]
	v_mfma_f32_16x16x32_bf16 v[52:55], v[148:151], v[192:195], v[52:55]
	v_mfma_f32_16x16x32_bf16 v[52:55], v[144:147], v[188:191], v[52:55]
	v_mfma_f32_16x16x32_bf16 v[36:39], v[144:147], v[196:199], v[36:39]
	v_mfma_f32_16x16x32_bf16 v[36:39], v[148:151], v[200:203], v[36:39]
	v_mfma_f32_16x16x32_bf16 v[32:35], v[156:159], v[200:203], v[32:35]
	v_mfma_f32_16x16x32_bf16 v[32:35], v[152:155], v[196:199], v[32:35]
	v_mfma_f32_16x16x32_bf16 v[12:15], v[160:163], v[196:199], v[12:15]
	v_mfma_f32_16x16x32_bf16 v[12:15], v[164:167], v[200:203], v[12:15]
	v_mfma_f32_16x16x32_bf16 v[8:11], v[176:179], v[200:203], v[8:11]
	v_mfma_f32_16x16x32_bf16 v[8:11], v[172:175], v[196:199], v[8:11]
	v_mfma_f32_16x16x32_bf16 v[0:3], v[172:175], v[204:207], v[0:3]
	v_mfma_f32_16x16x32_bf16 v[0:3], v[176:179], v[212:215], v[0:3]
	v_mfma_f32_16x16x32_bf16 v[4:7], v[164:167], v[212:215], v[4:7]
	v_mfma_f32_16x16x32_bf16 v[4:7], v[160:163], v[204:207], v[4:7]
	v_mfma_f32_16x16x32_bf16 v[16:19], v[152:155], v[204:207], v[16:19]
	v_mfma_f32_16x16x32_bf16 v[16:19], v[156:159], v[212:215], v[16:19]
	v_mfma_f32_16x16x32_bf16 v[20:23], v[148:151], v[212:215], v[20:23]
	v_mfma_f32_16x16x32_bf16 v[20:23], v[144:147], v[204:207], v[20:23]
	s_barrier
	s_mov_b32 m0, s41
	v_lshl_add_u64 v[218:219], v[216:217], 0, s[4:5]
	global_load_lds_dwordx4 v[218:219], off
	v_lshl_add_u64 v[218:219], v[216:217], 0, s[6:7]
	s_mov_b32 m0, s42
	s_nop 0
	global_load_lds_dwordx4 v[218:219], off
	s_add_i32 s56, 0, 0x18000
	v_add_u32_e32 v143, s56, v139
	s_add_i32 s57, 0, 0x1c000
	ds_read_b128 v[144:147], v143
	ds_read_b128 v[148:151], v143 offset:1024
	ds_read_b128 v[152:155], v143 offset:2048
	ds_read_b128 v[156:159], v143 offset:3072
	v_add_u32_e32 v143, s57, v139
	ds_read_b128 v[160:163], v143
	ds_read_b128 v[164:167], v143 offset:1024
	ds_read_b128 v[172:175], v143 offset:2048
	ds_read_b128 v[176:179], v143 offset:3072
	ds_read_b128 v[180:183], v142 offset:32768
	ds_read_b128 v[184:187], v142 offset:33792
	ds_read_b128 v[188:191], v142 offset:34816
	ds_read_b128 v[192:195], v142 offset:35840
	ds_read_b128 v[196:199], v142 offset:36864
	ds_read_b128 v[200:203], v142 offset:37888
	ds_read_b128 v[204:207], v142 offset:38912
	ds_read_b128 v[212:215], v142 offset:39936
	s_nop 0
	s_waitcnt vmcnt(8)
	s_waitcnt lgkmcnt(0)
	s_barrier
	s_waitcnt lgkmcnt(0)
	v_mfma_f32_16x16x32_bf16 v[124:127], v[144:147], v[180:183], v[124:127]
	v_mfma_f32_16x16x32_bf16 v[124:127], v[148:151], v[184:187], v[124:127]
	v_mfma_f32_16x16x32_bf16 v[120:123], v[156:159], v[184:187], v[120:123]
	v_mfma_f32_16x16x32_bf16 v[120:123], v[152:155], v[180:183], v[120:123]
	v_mfma_f32_16x16x32_bf16 v[108:111], v[160:163], v[180:183], v[108:111]
	v_mfma_f32_16x16x32_bf16 v[108:111], v[164:167], v[184:187], v[108:111]
	v_mfma_f32_16x16x32_bf16 v[104:107], v[176:179], v[184:187], v[104:107]
	v_mfma_f32_16x16x32_bf16 v[104:107], v[172:175], v[180:183], v[104:107]
	v_mfma_f32_16x16x32_bf16 v[88:91], v[172:175], v[188:191], v[88:91]
	v_mfma_f32_16x16x32_bf16 v[88:91], v[176:179], v[192:195], v[88:91]
	v_mfma_f32_16x16x32_bf16 v[92:95], v[164:167], v[192:195], v[92:95]
	v_mfma_f32_16x16x32_bf16 v[92:95], v[160:163], v[188:191], v[92:95]
	v_mfma_f32_16x16x32_bf16 v[112:115], v[152:155], v[188:191], v[112:115]
	v_mfma_f32_16x16x32_bf16 v[112:115], v[156:159], v[192:195], v[112:115]
	v_mfma_f32_16x16x32_bf16 v[116:119], v[148:151], v[192:195], v[116:119]
	v_mfma_f32_16x16x32_bf16 v[116:119], v[144:147], v[188:191], v[116:119]
	v_mfma_f32_16x16x32_bf16 v[100:103], v[144:147], v[196:199], v[100:103]
	v_mfma_f32_16x16x32_bf16 v[100:103], v[148:151], v[200:203], v[100:103]
	v_mfma_f32_16x16x32_bf16 v[96:99], v[156:159], v[200:203], v[96:99]
	v_mfma_f32_16x16x32_bf16 v[96:99], v[152:155], v[196:199], v[96:99]
	v_mfma_f32_16x16x32_bf16 v[76:79], v[160:163], v[196:199], v[76:79]
	v_mfma_f32_16x16x32_bf16 v[76:79], v[164:167], v[200:203], v[76:79]
	v_mfma_f32_16x16x32_bf16 v[72:75], v[176:179], v[200:203], v[72:75]
	v_mfma_f32_16x16x32_bf16 v[72:75], v[172:175], v[196:199], v[72:75]
	v_mfma_f32_16x16x32_bf16 v[64:67], v[172:175], v[204:207], v[64:67]
	v_mfma_f32_16x16x32_bf16 v[64:67], v[176:179], v[212:215], v[64:67]
	v_mfma_f32_16x16x32_bf16 v[68:71], v[164:167], v[212:215], v[68:71]
	v_mfma_f32_16x16x32_bf16 v[68:71], v[160:163], v[204:207], v[68:71]
	v_mfma_f32_16x16x32_bf16 v[80:83], v[152:155], v[204:207], v[80:83]
	v_mfma_f32_16x16x32_bf16 v[80:83], v[156:159], v[212:215], v[80:83]
	v_mfma_f32_16x16x32_bf16 v[84:87], v[148:151], v[212:215], v[84:87]
	v_mfma_f32_16x16x32_bf16 v[84:87], v[144:147], v[204:207], v[84:87]
	s_barrier
	s_add_i32 s56, s56, s38
	v_lshl_add_u64 v[218:219], v[208:209], 0, s[12:13]
	s_mov_b32 m0, s56
	s_nop 0
	global_load_lds_dwordx4 v[218:219], off
	v_lshl_add_u64 v[218:219], v[208:209], 0, s[14:15]
	s_add_i32 m0, s56, 0x2000
	s_add_i32 s56, s57, s38
	global_load_lds_dwordx4 v[218:219], off
	v_lshl_add_u64 v[218:219], v[208:209], 0, s[16:17]
	s_mov_b32 m0, s56
	v_lshl_add_u64 v[208:209], v[208:209], 0, s[18:19]
	global_load_lds_dwordx4 v[218:219], off
	s_add_i32 m0, s56, 0x2000
	s_nop 0
	global_load_lds_dwordx4 v[208:209], off
	v_lshl_add_u64 v[208:209], v[216:217], 0, s[12:13]
	s_mov_b32 m0, s44
	s_nop 0
	global_load_lds_dwordx4 v[208:209], off
	v_lshl_add_u64 v[208:209], v[216:217], 0, s[14:15]
	s_mov_b32 m0, s45
	s_nop 0
	global_load_lds_dwordx4 v[208:209], off
	ds_read_b128 v[180:183], v142 offset:49152
	ds_read_b128 v[184:187], v142 offset:50176
	ds_read_b128 v[188:191], v142 offset:51200
	ds_read_b128 v[192:195], v142 offset:52224
	ds_read_b128 v[196:199], v142 offset:53248
	ds_read_b128 v[200:203], v142 offset:54272
	ds_read_b128 v[204:207], v142 offset:55296
	ds_read_b128 v[212:215], v142 offset:56320
	s_waitcnt vmcnt(8)
	s_waitcnt lgkmcnt(0)
	s_barrier
	s_waitcnt lgkmcnt(0)
	v_mfma_f32_16x16x32_bf16 v[60:63], v[144:147], v[180:183], v[60:63]
	v_mfma_f32_16x16x32_bf16 v[60:63], v[148:151], v[184:187], v[60:63]
	v_mfma_f32_16x16x32_bf16 v[56:59], v[156:159], v[184:187], v[56:59]
	v_mfma_f32_16x16x32_bf16 v[56:59], v[152:155], v[180:183], v[56:59]
	v_mfma_f32_16x16x32_bf16 v[44:47], v[160:163], v[180:183], v[44:47]
	v_mfma_f32_16x16x32_bf16 v[44:47], v[164:167], v[184:187], v[44:47]
	v_mfma_f32_16x16x32_bf16 v[40:43], v[176:179], v[184:187], v[40:43]
	v_mfma_f32_16x16x32_bf16 v[40:43], v[172:175], v[180:183], v[40:43]
	v_mfma_f32_16x16x32_bf16 v[24:27], v[172:175], v[188:191], v[24:27]
	v_mfma_f32_16x16x32_bf16 v[24:27], v[176:179], v[192:195], v[24:27]
	v_mfma_f32_16x16x32_bf16 v[28:31], v[164:167], v[192:195], v[28:31]
	v_mfma_f32_16x16x32_bf16 v[28:31], v[160:163], v[188:191], v[28:31]
	v_mfma_f32_16x16x32_bf16 v[48:51], v[152:155], v[188:191], v[48:51]
	v_mfma_f32_16x16x32_bf16 v[48:51], v[156:159], v[192:195], v[48:51]
	v_mfma_f32_16x16x32_bf16 v[52:55], v[148:151], v[192:195], v[52:55]
	v_mfma_f32_16x16x32_bf16 v[52:55], v[144:147], v[188:191], v[52:55]
	v_mfma_f32_16x16x32_bf16 v[36:39], v[144:147], v[196:199], v[36:39]
	v_mfma_f32_16x16x32_bf16 v[36:39], v[148:151], v[200:203], v[36:39]
	v_mfma_f32_16x16x32_bf16 v[32:35], v[156:159], v[200:203], v[32:35]
	v_mfma_f32_16x16x32_bf16 v[32:35], v[152:155], v[196:199], v[32:35]
	v_mfma_f32_16x16x32_bf16 v[12:15], v[160:163], v[196:199], v[12:15]
	v_mfma_f32_16x16x32_bf16 v[12:15], v[164:167], v[200:203], v[12:15]
	v_mfma_f32_16x16x32_bf16 v[8:11], v[176:179], v[200:203], v[8:11]
	v_mfma_f32_16x16x32_bf16 v[8:11], v[172:175], v[196:199], v[8:11]
	v_mfma_f32_16x16x32_bf16 v[0:3], v[172:175], v[204:207], v[0:3]
	v_mfma_f32_16x16x32_bf16 v[0:3], v[176:179], v[212:215], v[0:3]
	v_mfma_f32_16x16x32_bf16 v[4:7], v[164:167], v[212:215], v[4:7]
	v_mfma_f32_16x16x32_bf16 v[4:7], v[160:163], v[204:207], v[4:7]
	v_mfma_f32_16x16x32_bf16 v[16:19], v[152:155], v[204:207], v[16:19]
	v_mfma_f32_16x16x32_bf16 v[16:19], v[156:159], v[212:215], v[16:19]
	v_mfma_f32_16x16x32_bf16 v[20:23], v[148:151], v[212:215], v[20:23]
	v_mfma_f32_16x16x32_bf16 v[20:23], v[144:147], v[204:207], v[20:23]
	s_barrier
	s_cmp_gt_u32 s55, 41
	s_cbranch_scc0 .LBB0_1046
	s_and_b64 vcc, exec, s[20:21]
	s_cbranch_vccz .LBB0_1049
	s_barrier
